# + LDS fragment base addresses hoisted out of the K-loops (last 4 VALU per iteration removed)
# baseline (speedup 1.0000x reference)
; #define PG8_STAGE(bufoff, gbase, voff) do { _Pragma("unroll") for (int _i = 0; _i < 2; ++_i) \
;         __builtin_amdgcn_global_load_lds((const unsigned*)((const char*)(gbase) + (voff)[_i]), (PG8_LAS unsigned*)(lds + (bufoff) + ldsw + _i * 8192), 16, 0, 0); } while (0)
; #define PG8_LDA(dst, b, h) do { _Pragma("unroll") for (int m = 0; m < 4; ++m) _Pragma("unroll") for (int k = 0; k < 2; ++k) dst[m][k] = *(const PG8_LAS bf16x8*)(lds + PG8_SA(b, h) + aoff + m * 2048 + k * 1024); } while (0)
; #define PG8_LDB(dst, b, h) do { _Pragma("unroll") for (int n = 0; n < 2; ++n) _Pragma("unroll") for (int k = 0; k < 2; ++k) dst[n][k] = *(const PG8_LAS bf16x8*)(lds + PG8_SB(b, h) + boff + n * 2048 + k * 1024); } while (0)
; #define PG8_WAIT_V(n) asm volatile("s_waitcnt vmcnt(" #n ")" ::: "memory")
; #define PG8_WAIT_L(n) asm volatile("s_waitcnt lgkmcnt(" #n ")" ::: "memory")
; #define PG8_BAR __builtin_amdgcn_s_barrier()
; template <class Epi, class Sched, bool ALIGN_EPI = false, bool SP2 = false, bool F8 = false>
; __device__ __forceinline__ void gemm_phase(PG8_LAS unsigned char* lds, const int K, const Sched& S, const Epi& E, const int wave) {
;     ...
;             const bool last = (t == nt - 2);
;             const char* a1 = cA + (size_t)(t + 1) * kstep;
;             const char* a2 = last ? nA : cA + (size_t)(t + 2) * kstep; const char* b2 = last ? nB : cB + (size_t)(t + 2) * kstep;
;             const char* a3 = a2 + kstep; const char* b3 = b2 + kstep;
;             asm volatile("" : "+s"(a1), "+s"(a2), "+s"(b2), "+s"(a3), "+s"(b3));
;             if (last && has_next) S.a_ready(nxt);
;             if constexpr (Epi::KHOOK) { if (cur.prob == 2 ? (t == 16) : (t == 32 || t == 48)) { if (wr == 0) PG8_BAR;
;                 E.khook(acc, cur, (cur.prob == 2 || t == 48) ? 1 : 0, wr, wc, fr, fq); if (wr == 1) PG8_BAR; } }
;             if constexpr (SP2) {
;             PG8_LDB(B0, 0, 0); PG8_LDB(B1, 0, 1); PG8_SCHED; PG8_LDA(At, 0, 0); PG8_STAGE(PG8_SA(1, 1), a1 + hstep, voffA);
;             PG8_WAIT_V(8); PG8_WAIT_L(0); PG8_BAR; PG8_MMA(0, 0, At, B0); PG8_MMA(0, 1, At, B1); PG8_BAR; PG8_SCHED;
;             PG8_LDA(At, 0, 1); PG8_STAGE(PG8_SB(0, 0), b2, voffB); PG8_STAGE(PG8_SB(0, 1), b2 + hstep, voffB); PG8_STAGE(PG8_SA(0, 0), a2, voffA);
;             PG8_WAIT_V(8); PG8_WAIT_L(0); PG8_BAR; PG8_MMA(1, 0, At, B0); PG8_MMA(1, 1, At, B1); PG8_BAR; PG8_SCHED;
.Lpeel_k186:
	v_add_u32_e32 v193, s47, v245
	v_add_u32_e32 v195, s41, v245
	v_add_u32_e32 v197, 0x18000, v245
	v_add_u32_e32 v199, 0x1c000, v245
	s_add_u32 s6, s14, s0
	s_addc_u32 s7, s15, s1
	s_add_u32 s64, s6, 0xffffff80
	s_addc_u32 s65, s7, -1
	s_add_u32 s76, s36, s0
	s_addc_u32 s77, s37, s1
	s_cmp_eq_u32 vcc_lo, 60
	s_cselect_b32 s94, s85, s6
	s_cselect_b32 s95, s83, s7
	s_cselect_b32 s7, s96, s77
	s_cselect_b32 s6, s97, s76
	s_add_u32 s78, s94, 0x80
	s_addc_u32 s79, s95, 0
	s_add_u32 s76, s6, 0x80
	s_addc_u32 s77, s7, 0
	ds_read_b128 v[128:131], v193
	ds_read_b128 v[132:135], v193 offset:1024
	ds_read_b128 v[136:139], v193 offset:2048
	ds_read_b128 v[140:143], v193 offset:3072
	ds_read_b128 v[144:147], v195
	ds_read_b128 v[148:151], v195 offset:1024
	ds_read_b128 v[152:155], v195 offset:2048
	ds_read_b128 v[156:159], v195 offset:3072
	s_add_u32 s64, s64, 0x100000
	s_addc_u32 s65, s65, 0
	s_add_i32 m0, s13, 0xc000
	ds_read_b128 v[160:163], v248
	ds_read_b128 v[164:167], v248 offset:1024
	ds_read_b128 v[168:171], v248 offset:2048
	ds_read_b128 v[172:175], v248 offset:3072
	ds_read_b128 v[176:179], v248 offset:4096
	ds_read_b128 v[180:183], v248 offset:5120
	ds_read_b128 v[184:187], v248 offset:6144
	ds_read_b128 v[188:191], v248 offset:7168
	global_load_lds_dwordx4 v192, s[64:65]
	s_add_i32 m0, s13, 0xe000
	s_nop 0
	global_load_lds_dwordx4 v196, s[64:65]
	s_waitcnt vmcnt(8)
	s_waitcnt lgkmcnt(0)
	s_setprio 1
	s_barrier
	v_mfma_f32_16x16x32_bf16 v[124:127], v[128:131], v[160:163], 0
	v_mfma_f32_16x16x32_bf16 v[120:123], v[136:139], v[160:163], 0
	v_mfma_f32_16x16x32_bf16 v[116:119], v[128:131], v[168:171], 0
	v_mfma_f32_16x16x32_bf16 v[112:115], v[136:139], v[168:171], 0
	v_mfma_f32_16x16x32_bf16 v[108:111], v[128:131], v[176:179], 0
	v_mfma_f32_16x16x32_bf16 v[104:107], v[136:139], v[176:179], 0
	v_mfma_f32_16x16x32_bf16 v[100:103], v[128:131], v[184:187], 0
	v_mfma_f32_16x16x32_bf16 v[96:99], v[136:139], v[184:187], 0
	v_mfma_f32_16x16x32_bf16 v[124:127], v[132:135], v[164:167], v[124:127]
	v_mfma_f32_16x16x32_bf16 v[120:123], v[140:143], v[164:167], v[120:123]
	v_mfma_f32_16x16x32_bf16 v[116:119], v[132:135], v[172:175], v[116:119]
	v_mfma_f32_16x16x32_bf16 v[112:115], v[140:143], v[172:175], v[112:115]
	v_mfma_f32_16x16x32_bf16 v[108:111], v[132:135], v[180:183], v[108:111]
	v_mfma_f32_16x16x32_bf16 v[104:107], v[140:143], v[180:183], v[104:107]
	v_mfma_f32_16x16x32_bf16 v[100:103], v[132:135], v[188:191], v[100:103]
	v_mfma_f32_16x16x32_bf16 v[96:99], v[140:143], v[188:191], v[96:99]
	v_mfma_f32_16x16x32_bf16 v[92:95], v[144:147], v[160:163], 0
	v_mfma_f32_16x16x32_bf16 v[88:91], v[152:155], v[160:163], 0
	v_mfma_f32_16x16x32_bf16 v[84:87], v[144:147], v[168:171], 0
	v_mfma_f32_16x16x32_bf16 v[80:83], v[152:155], v[168:171], 0
	v_mfma_f32_16x16x32_bf16 v[76:79], v[144:147], v[176:179], 0
	v_mfma_f32_16x16x32_bf16 v[72:75], v[152:155], v[176:179], 0
	v_mfma_f32_16x16x32_bf16 v[68:71], v[144:147], v[184:187], 0
	v_mfma_f32_16x16x32_bf16 v[64:67], v[152:155], v[184:187], 0
	v_mfma_f32_16x16x32_bf16 v[92:95], v[148:151], v[164:167], v[92:95]
	v_mfma_f32_16x16x32_bf16 v[88:91], v[156:159], v[164:167], v[88:91]
	v_mfma_f32_16x16x32_bf16 v[84:87], v[148:151], v[172:175], v[84:87]
	v_mfma_f32_16x16x32_bf16 v[80:83], v[156:159], v[172:175], v[80:83]
	v_mfma_f32_16x16x32_bf16 v[76:79], v[148:151], v[180:183], v[76:79]
	v_mfma_f32_16x16x32_bf16 v[72:75], v[156:159], v[180:183], v[72:75]
	v_mfma_f32_16x16x32_bf16 v[68:71], v[148:151], v[188:191], v[68:71]
	v_mfma_f32_16x16x32_bf16 v[64:67], v[156:159], v[188:191], v[64:67]
	s_barrier
	s_setprio 0
	s_add_i32 s64, s47, s74
	s_mov_b32 m0, s64
	ds_read_b128 v[160:163], v248 offset:16384
	ds_read_b128 v[164:167], v248 offset:17408
	ds_read_b128 v[168:171], v248 offset:18432
	ds_read_b128 v[172:175], v248 offset:19456
	ds_read_b128 v[176:179], v248 offset:20480
	ds_read_b128 v[180:183], v248 offset:21504
	ds_read_b128 v[184:187], v248 offset:22528
	ds_read_b128 v[188:191], v248 offset:23552
	global_load_lds_dwordx4 v194, s[6:7]
	s_add_i32 m0, s64, 0x2000
	s_nop 0
	global_load_lds_dwordx4 v198, s[6:7]
	s_add_u32 s6, s6, 0x100000
	s_addc_u32 s7, s7, 0
	s_add_i32 s64, s41, s74
	s_mov_b32 m0, s64
	s_nop 0
	global_load_lds_dwordx4 v194, s[6:7]
	s_add_i32 m0, s64, 0x2000
	s_nop 0
	global_load_lds_dwordx4 v198, s[6:7]
	s_mov_b32 m0, s13
	s_nop 0
	global_load_lds_dwordx4 v192, s[94:95]
	s_mov_b32 m0, s51
	s_nop 0
	global_load_lds_dwordx4 v196, s[94:95]
	s_waitcnt vmcnt(8)
	s_waitcnt lgkmcnt(0)
	s_setprio 1
	s_barrier
	v_mfma_f32_16x16x32_bf16 v[60:63], v[128:131], v[160:163], 0
	v_mfma_f32_16x16x32_bf16 v[56:59], v[136:139], v[160:163], 0
	v_mfma_f32_16x16x32_bf16 v[52:55], v[128:131], v[168:171], 0
	v_mfma_f32_16x16x32_bf16 v[48:51], v[136:139], v[168:171], 0
	v_mfma_f32_16x16x32_bf16 v[44:47], v[128:131], v[176:179], 0
	v_mfma_f32_16x16x32_bf16 v[40:43], v[136:139], v[176:179], 0
	v_mfma_f32_16x16x32_bf16 v[36:39], v[128:131], v[184:187], 0
	v_mfma_f32_16x16x32_bf16 v[32:35], v[136:139], v[184:187], 0
	v_mfma_f32_16x16x32_bf16 v[60:63], v[132:135], v[164:167], v[60:63]
	v_mfma_f32_16x16x32_bf16 v[56:59], v[140:143], v[164:167], v[56:59]
	v_mfma_f32_16x16x32_bf16 v[52:55], v[132:135], v[172:175], v[52:55]
	v_mfma_f32_16x16x32_bf16 v[48:51], v[140:143], v[172:175], v[48:51]
	v_mfma_f32_16x16x32_bf16 v[44:47], v[132:135], v[180:183], v[44:47]
	v_mfma_f32_16x16x32_bf16 v[40:43], v[140:143], v[180:183], v[40:43]
	v_mfma_f32_16x16x32_bf16 v[36:39], v[132:135], v[188:191], v[36:39]
	v_mfma_f32_16x16x32_bf16 v[32:35], v[140:143], v[188:191], v[32:35]
	v_mfma_f32_16x16x32_bf16 v[28:31], v[144:147], v[160:163], 0
	v_mfma_f32_16x16x32_bf16 v[24:27], v[152:155], v[160:163], 0
	v_mfma_f32_16x16x32_bf16 v[20:23], v[144:147], v[168:171], 0
	v_mfma_f32_16x16x32_bf16 v[16:19], v[152:155], v[168:171], 0
	v_mfma_f32_16x16x32_bf16 v[12:15], v[144:147], v[176:179], 0
	v_mfma_f32_16x16x32_bf16 v[8:11], v[152:155], v[176:179], 0
	v_mfma_f32_16x16x32_bf16 v[4:7], v[144:147], v[184:187], 0
	v_mfma_f32_16x16x32_bf16 v[0:3], v[152:155], v[184:187], 0
	v_mfma_f32_16x16x32_bf16 v[28:31], v[148:151], v[164:167], v[28:31]
	v_mfma_f32_16x16x32_bf16 v[24:27], v[156:159], v[164:167], v[24:27]
	v_mfma_f32_16x16x32_bf16 v[20:23], v[148:151], v[172:175], v[20:23]
	v_mfma_f32_16x16x32_bf16 v[16:19], v[156:159], v[172:175], v[16:19]
	v_mfma_f32_16x16x32_bf16 v[12:15], v[148:151], v[180:183], v[12:15]
	v_mfma_f32_16x16x32_bf16 v[8:11], v[156:159], v[180:183], v[8:11]
	v_mfma_f32_16x16x32_bf16 v[4:7], v[148:151], v[188:191], v[4:7]
	v_mfma_f32_16x16x32_bf16 v[0:3], v[156:159], v[188:191], v[0:3]
	s_barrier
	s_branch .Lmid_k186
; #define PG8_STAGE(bufoff, gbase, voff) do { _Pragma("unroll") for (int _i = 0; _i < 2; ++_i) \
;         __builtin_amdgcn_global_load_lds((const unsigned*)((const char*)(gbase) + (voff)[_i]), (PG8_LAS unsigned*)(lds + (bufoff) + ldsw + _i * 8192), 16, 0, 0); } while (0)
; #define PG8_LDA(dst, b, h) do { _Pragma("unroll") for (int m = 0; m < 4; ++m) _Pragma("unroll") for (int k = 0; k < 2; ++k) dst[m][k] = *(const PG8_LAS bf16x8*)(lds + PG8_SA(b, h) + aoff + m * 2048 + k * 1024); } while (0)
; #define PG8_LDB(dst, b, h) do { _Pragma("unroll") for (int n = 0; n < 2; ++n) _Pragma("unroll") for (int k = 0; k < 2; ++k) dst[n][k] = *(const PG8_LAS bf16x8*)(lds + PG8_SB(b, h) + boff + n * 2048 + k * 1024); } while (0)
; #define PG8_WAIT_V(n) asm volatile("s_waitcnt vmcnt(" #n ")" ::: "memory")
; #define PG8_WAIT_L(n) asm volatile("s_waitcnt lgkmcnt(" #n ")" ::: "memory")
; #define PG8_BAR __builtin_amdgcn_s_barrier()
; template <class Epi, class Sched, bool ALIGN_EPI = false, bool SP2 = false, bool F8 = false>
; __device__ __forceinline__ void gemm_phase(PG8_LAS unsigned char* lds, const int K, const Sched& S, const Epi& E, const int wave) {
;     ...
;             const bool last = (t == nt - 2);
;             const char* a1 = cA + (size_t)(t + 1) * kstep;
;             const char* a2 = last ? nA : cA + (size_t)(t + 2) * kstep; const char* b2 = last ? nB : cB + (size_t)(t + 2) * kstep;
;             const char* a3 = a2 + kstep; const char* b3 = b2 + kstep;
;             asm volatile("" : "+s"(a1), "+s"(a2), "+s"(b2), "+s"(a3), "+s"(b3));
;             if (last && has_next) S.a_ready(nxt);
;             if constexpr (Epi::KHOOK) { if (cur.prob == 2 ? (t == 16) : (t == 32 || t == 48)) { if (wr == 0) PG8_BAR;
;                 E.khook(acc, cur, (cur.prob == 2 || t == 48) ? 1 : 0, wr, wc, fr, fq); if (wr == 1) PG8_BAR; } }
;             if constexpr (SP2) {
;             PG8_LDB(B0, 0, 0); PG8_LDB(B1, 0, 1); PG8_SCHED; PG8_LDA(At, 0, 0); PG8_STAGE(PG8_SA(1, 1), a1 + hstep, voffA);
;             PG8_WAIT_V(8); PG8_WAIT_L(0); PG8_BAR; PG8_MMA(0, 0, At, B0); PG8_MMA(0, 1, At, B1); PG8_BAR; PG8_SCHED;
;             PG8_LDA(At, 0, 1); PG8_STAGE(PG8_SB(0, 0), b2, voffB); PG8_STAGE(PG8_SB(0, 1), b2 + hstep, voffB); PG8_STAGE(PG8_SA(0, 0), a2, voffA);
;             PG8_WAIT_V(8); PG8_WAIT_L(0); PG8_BAR; PG8_MMA(1, 0, At, B0); PG8_MMA(1, 1, At, B1); PG8_BAR; PG8_SCHED;
.LBB0_186:
	s_add_u32 s6, s14, s0
	s_addc_u32 s7, s15, s1
	s_add_u32 s64, s6, 0xffffff80
	s_addc_u32 s65, s7, -1
	s_add_u32 s76, s36, s0
	s_addc_u32 s77, s37, s1
	s_cmp_eq_u32 vcc_lo, 60
	s_cselect_b32 s94, s85, s6
	s_cselect_b32 s95, s83, s7
	s_cselect_b32 s7, s96, s77
	s_cselect_b32 s6, s97, s76
	s_add_u32 s78, s94, 0x80
	s_addc_u32 s79, s95, 0
	s_add_u32 s76, s6, 0x80
	s_addc_u32 s77, s7, 0
	ds_read_b128 v[128:131], v193
	ds_read_b128 v[132:135], v193 offset:1024
	ds_read_b128 v[136:139], v193 offset:2048
	ds_read_b128 v[140:143], v193 offset:3072
	ds_read_b128 v[144:147], v195
	ds_read_b128 v[148:151], v195 offset:1024
	ds_read_b128 v[152:155], v195 offset:2048
	ds_read_b128 v[156:159], v195 offset:3072
	s_add_u32 s64, s64, 0x100000
	s_addc_u32 s65, s65, 0
	s_add_i32 m0, s13, 0xc000
	ds_read_b128 v[160:163], v248
	ds_read_b128 v[164:167], v248 offset:1024
	ds_read_b128 v[168:171], v248 offset:2048
	ds_read_b128 v[172:175], v248 offset:3072
	ds_read_b128 v[176:179], v248 offset:4096
	ds_read_b128 v[180:183], v248 offset:5120
	ds_read_b128 v[184:187], v248 offset:6144
	ds_read_b128 v[188:191], v248 offset:7168
	global_load_lds_dwordx4 v192, s[64:65]
	s_add_i32 m0, s13, 0xe000
	s_nop 0
	global_load_lds_dwordx4 v196, s[64:65]
	s_waitcnt vmcnt(8)
	s_waitcnt lgkmcnt(0)
	s_setprio 1
	s_barrier
	v_mfma_f32_16x16x32_bf16 v[124:127], v[128:131], v[160:163], v[124:127]
	v_mfma_f32_16x16x32_bf16 v[120:123], v[136:139], v[160:163], v[120:123]
	v_mfma_f32_16x16x32_bf16 v[116:119], v[128:131], v[168:171], v[116:119]
	v_mfma_f32_16x16x32_bf16 v[112:115], v[136:139], v[168:171], v[112:115]
	v_mfma_f32_16x16x32_bf16 v[108:111], v[128:131], v[176:179], v[108:111]
	v_mfma_f32_16x16x32_bf16 v[104:107], v[136:139], v[176:179], v[104:107]
	v_mfma_f32_16x16x32_bf16 v[100:103], v[128:131], v[184:187], v[100:103]
	v_mfma_f32_16x16x32_bf16 v[96:99], v[136:139], v[184:187], v[96:99]
	v_mfma_f32_16x16x32_bf16 v[124:127], v[132:135], v[164:167], v[124:127]
	v_mfma_f32_16x16x32_bf16 v[120:123], v[140:143], v[164:167], v[120:123]
	v_mfma_f32_16x16x32_bf16 v[116:119], v[132:135], v[172:175], v[116:119]
	v_mfma_f32_16x16x32_bf16 v[112:115], v[140:143], v[172:175], v[112:115]
	v_mfma_f32_16x16x32_bf16 v[108:111], v[132:135], v[180:183], v[108:111]
	v_mfma_f32_16x16x32_bf16 v[104:107], v[140:143], v[180:183], v[104:107]
	v_mfma_f32_16x16x32_bf16 v[100:103], v[132:135], v[188:191], v[100:103]
	v_mfma_f32_16x16x32_bf16 v[96:99], v[140:143], v[188:191], v[96:99]
	v_mfma_f32_16x16x32_bf16 v[92:95], v[144:147], v[160:163], v[92:95]
	v_mfma_f32_16x16x32_bf16 v[88:91], v[152:155], v[160:163], v[88:91]
	v_mfma_f32_16x16x32_bf16 v[84:87], v[144:147], v[168:171], v[84:87]
	v_mfma_f32_16x16x32_bf16 v[80:83], v[152:155], v[168:171], v[80:83]
	v_mfma_f32_16x16x32_bf16 v[76:79], v[144:147], v[176:179], v[76:79]
	v_mfma_f32_16x16x32_bf16 v[72:75], v[152:155], v[176:179], v[72:75]
	v_mfma_f32_16x16x32_bf16 v[68:71], v[144:147], v[184:187], v[68:71]
	v_mfma_f32_16x16x32_bf16 v[64:67], v[152:155], v[184:187], v[64:67]
	v_mfma_f32_16x16x32_bf16 v[92:95], v[148:151], v[164:167], v[92:95]
	v_mfma_f32_16x16x32_bf16 v[88:91], v[156:159], v[164:167], v[88:91]
	v_mfma_f32_16x16x32_bf16 v[84:87], v[148:151], v[172:175], v[84:87]
	v_mfma_f32_16x16x32_bf16 v[80:83], v[156:159], v[172:175], v[80:83]
	v_mfma_f32_16x16x32_bf16 v[76:79], v[148:151], v[180:183], v[76:79]
	v_mfma_f32_16x16x32_bf16 v[72:75], v[156:159], v[180:183], v[72:75]
	v_mfma_f32_16x16x32_bf16 v[68:71], v[148:151], v[188:191], v[68:71]
	v_mfma_f32_16x16x32_bf16 v[64:67], v[156:159], v[188:191], v[64:67]
	s_barrier
	s_setprio 0
	s_add_i32 s64, s47, s74
	s_mov_b32 m0, s64
	ds_read_b128 v[160:163], v248 offset:16384
	ds_read_b128 v[164:167], v248 offset:17408
	ds_read_b128 v[168:171], v248 offset:18432
	ds_read_b128 v[172:175], v248 offset:19456
	ds_read_b128 v[176:179], v248 offset:20480
	ds_read_b128 v[180:183], v248 offset:21504
	ds_read_b128 v[184:187], v248 offset:22528
	ds_read_b128 v[188:191], v248 offset:23552
	global_load_lds_dwordx4 v194, s[6:7]
	s_add_i32 m0, s64, 0x2000
	s_nop 0
	global_load_lds_dwordx4 v198, s[6:7]
	s_add_u32 s6, s6, 0x100000
	s_addc_u32 s7, s7, 0
	s_add_i32 s64, s41, s74
	s_mov_b32 m0, s64
	s_nop 0
	global_load_lds_dwordx4 v194, s[6:7]
	s_add_i32 m0, s64, 0x2000
	s_nop 0
	global_load_lds_dwordx4 v198, s[6:7]
	s_mov_b32 m0, s13
	s_nop 0
	global_load_lds_dwordx4 v192, s[94:95]
	s_mov_b32 m0, s51
	s_nop 0
	global_load_lds_dwordx4 v196, s[94:95]
	s_waitcnt vmcnt(8)
	s_waitcnt lgkmcnt(0)
	s_setprio 1
	s_barrier
	v_mfma_f32_16x16x32_bf16 v[60:63], v[128:131], v[160:163], v[60:63]
	v_mfma_f32_16x16x32_bf16 v[56:59], v[136:139], v[160:163], v[56:59]
	v_mfma_f32_16x16x32_bf16 v[52:55], v[128:131], v[168:171], v[52:55]
	v_mfma_f32_16x16x32_bf16 v[48:51], v[136:139], v[168:171], v[48:51]
	v_mfma_f32_16x16x32_bf16 v[44:47], v[128:131], v[176:179], v[44:47]
	v_mfma_f32_16x16x32_bf16 v[40:43], v[136:139], v[176:179], v[40:43]
	v_mfma_f32_16x16x32_bf16 v[36:39], v[128:131], v[184:187], v[36:39]
	v_mfma_f32_16x16x32_bf16 v[32:35], v[136:139], v[184:187], v[32:35]
	v_mfma_f32_16x16x32_bf16 v[60:63], v[132:135], v[164:167], v[60:63]
	v_mfma_f32_16x16x32_bf16 v[56:59], v[140:143], v[164:167], v[56:59]
	v_mfma_f32_16x16x32_bf16 v[52:55], v[132:135], v[172:175], v[52:55]
	v_mfma_f32_16x16x32_bf16 v[48:51], v[140:143], v[172:175], v[48:51]
	v_mfma_f32_16x16x32_bf16 v[44:47], v[132:135], v[180:183], v[44:47]
	v_mfma_f32_16x16x32_bf16 v[40:43], v[140:143], v[180:183], v[40:43]
	v_mfma_f32_16x16x32_bf16 v[36:39], v[132:135], v[188:191], v[36:39]
	v_mfma_f32_16x16x32_bf16 v[32:35], v[140:143], v[188:191], v[32:35]
	v_mfma_f32_16x16x32_bf16 v[28:31], v[144:147], v[160:163], v[28:31]
	v_mfma_f32_16x16x32_bf16 v[24:27], v[152:155], v[160:163], v[24:27]
	v_mfma_f32_16x16x32_bf16 v[20:23], v[144:147], v[168:171], v[20:23]
	v_mfma_f32_16x16x32_bf16 v[16:19], v[152:155], v[168:171], v[16:19]
	v_mfma_f32_16x16x32_bf16 v[12:15], v[144:147], v[176:179], v[12:15]
	v_mfma_f32_16x16x32_bf16 v[8:11], v[152:155], v[176:179], v[8:11]
	v_mfma_f32_16x16x32_bf16 v[4:7], v[144:147], v[184:187], v[4:7]
	v_mfma_f32_16x16x32_bf16 v[0:3], v[152:155], v[184:187], v[0:3]
	v_mfma_f32_16x16x32_bf16 v[28:31], v[148:151], v[164:167], v[28:31]
	v_mfma_f32_16x16x32_bf16 v[24:27], v[156:159], v[164:167], v[24:27]
	v_mfma_f32_16x16x32_bf16 v[20:23], v[148:151], v[172:175], v[20:23]
	v_mfma_f32_16x16x32_bf16 v[16:19], v[156:159], v[172:175], v[16:19]
	v_mfma_f32_16x16x32_bf16 v[12:15], v[148:151], v[180:183], v[12:15]
	v_mfma_f32_16x16x32_bf16 v[8:11], v[156:159], v[180:183], v[8:11]
	v_mfma_f32_16x16x32_bf16 v[4:7], v[148:151], v[188:191], v[4:7]
	v_mfma_f32_16x16x32_bf16 v[0:3], v[156:159], v[188:191], v[0:3]
	s_barrier
; #define PG8_STAGE(bufoff, gbase, voff) do { _Pragma("unroll") for (int _i = 0; _i < 2; ++_i) \
;         __builtin_amdgcn_global_load_lds((const unsigned*)((const char*)(gbase) + (voff)[_i]), (PG8_LAS unsigned*)(lds + (bufoff) + ldsw + _i * 8192), 16, 0, 0); } while (0)
; #define PG8_LDA(dst, b, h) do { _Pragma("unroll") for (int m = 0; m < 4; ++m) _Pragma("unroll") for (int k = 0; k < 2; ++k) dst[m][k] = *(const PG8_LAS bf16x8*)(lds + PG8_SA(b, h) + aoff + m * 2048 + k * 1024); } while (0)
; #define PG8_LDB(dst, b, h) do { _Pragma("unroll") for (int n = 0; n < 2; ++n) _Pragma("unroll") for (int k = 0; k < 2; ++k) dst[n][k] = *(const PG8_LAS bf16x8*)(lds + PG8_SB(b, h) + boff + n * 2048 + k * 1024); } while (0)
; #define PG8_WAIT_V(n) asm volatile("s_waitcnt vmcnt(" #n ")" ::: "memory")
; #define PG8_WAIT_L(n) asm volatile("s_waitcnt lgkmcnt(" #n ")" ::: "memory")
; #define PG8_BAR __builtin_amdgcn_s_barrier()
; #define PG8_SCHED __builtin_amdgcn_sched_barrier(0)
; template <class Epi, class Sched, bool ALIGN_EPI = false, bool SP2 = false, bool F8 = false>
; __device__ __forceinline__ void gemm_phase(PG8_LAS unsigned char* lds, const int K, const Sched& S, const Epi& E, const int wave) {
;     ...
;             PG8_LDB(B0, 1, 0); PG8_LDB(B1, 1, 1); PG8_SCHED; PG8_LDA(At, 1, 0); PG8_STAGE(PG8_SA(0, 1), a2 + hstep, voffA);
;             PG8_WAIT_V(8); PG8_WAIT_L(0); PG8_BAR; PG8_MMA(0, 0, At, B0); PG8_MMA(0, 1, At, B1); PG8_BAR; PG8_SCHED;
;             PG8_LDA(At, 1, 1); PG8_STAGE(PG8_SB(1, 0), b3, voffB); PG8_STAGE(PG8_SB(1, 1), b3 + hstep, voffB); PG8_STAGE(PG8_SA(1, 0), a3, voffA);
;             PG8_WAIT_V(8); PG8_WAIT_L(0); PG8_BAR; PG8_MMA(1, 0, At, B0); PG8_MMA(1, 1, At, B1); PG8_BAR; PG8_SCHED;
.Lmid_k186:
	s_setprio 0
	s_add_i32 s64, 0, 0x18000
	s_add_i32 s65, 0, 0x1c000
	ds_read_b128 v[128:131], v197
	ds_read_b128 v[132:135], v197 offset:1024
	ds_read_b128 v[136:139], v197 offset:2048
	ds_read_b128 v[140:143], v197 offset:3072
	ds_read_b128 v[144:147], v199
	ds_read_b128 v[148:151], v199 offset:1024
	ds_read_b128 v[152:155], v199 offset:2048
	ds_read_b128 v[156:159], v199 offset:3072
	s_add_u32 s6, s94, 0x100000
	s_addc_u32 s7, s95, 0
	s_mov_b32 m0, s75
	ds_read_b128 v[160:163], v248 offset:32768
	ds_read_b128 v[164:167], v248 offset:33792
	ds_read_b128 v[168:171], v248 offset:34816
	ds_read_b128 v[172:175], v248 offset:35840
	ds_read_b128 v[176:179], v248 offset:36864
	ds_read_b128 v[180:183], v248 offset:37888
	ds_read_b128 v[184:187], v248 offset:38912
	ds_read_b128 v[188:191], v248 offset:39936
	global_load_lds_dwordx4 v192, s[6:7]
	s_mov_b32 m0, s48
	s_nop 0
	global_load_lds_dwordx4 v196, s[6:7]
	s_waitcnt vmcnt(8)
	s_waitcnt lgkmcnt(0)
	s_setprio 1
	s_barrier
	v_mfma_f32_16x16x32_bf16 v[124:127], v[128:131], v[160:163], v[124:127]
	v_mfma_f32_16x16x32_bf16 v[120:123], v[136:139], v[160:163], v[120:123]
	v_mfma_f32_16x16x32_bf16 v[116:119], v[128:131], v[168:171], v[116:119]
	v_mfma_f32_16x16x32_bf16 v[112:115], v[136:139], v[168:171], v[112:115]
	v_mfma_f32_16x16x32_bf16 v[108:111], v[128:131], v[176:179], v[108:111]
	v_mfma_f32_16x16x32_bf16 v[104:107], v[136:139], v[176:179], v[104:107]
	v_mfma_f32_16x16x32_bf16 v[100:103], v[128:131], v[184:187], v[100:103]
	v_mfma_f32_16x16x32_bf16 v[96:99], v[136:139], v[184:187], v[96:99]
	v_mfma_f32_16x16x32_bf16 v[124:127], v[132:135], v[164:167], v[124:127]
	v_mfma_f32_16x16x32_bf16 v[120:123], v[140:143], v[164:167], v[120:123]
	v_mfma_f32_16x16x32_bf16 v[116:119], v[132:135], v[172:175], v[116:119]
	v_mfma_f32_16x16x32_bf16 v[112:115], v[140:143], v[172:175], v[112:115]
	v_mfma_f32_16x16x32_bf16 v[108:111], v[132:135], v[180:183], v[108:111]
	v_mfma_f32_16x16x32_bf16 v[104:107], v[140:143], v[180:183], v[104:107]
	v_mfma_f32_16x16x32_bf16 v[100:103], v[132:135], v[188:191], v[100:103]
	v_mfma_f32_16x16x32_bf16 v[96:99], v[140:143], v[188:191], v[96:99]
	v_mfma_f32_16x16x32_bf16 v[92:95], v[144:147], v[160:163], v[92:95]
	v_mfma_f32_16x16x32_bf16 v[88:91], v[152:155], v[160:163], v[88:91]
	v_mfma_f32_16x16x32_bf16 v[84:87], v[144:147], v[168:171], v[84:87]
	v_mfma_f32_16x16x32_bf16 v[80:83], v[152:155], v[168:171], v[80:83]
	v_mfma_f32_16x16x32_bf16 v[76:79], v[144:147], v[176:179], v[76:79]
	v_mfma_f32_16x16x32_bf16 v[72:75], v[152:155], v[176:179], v[72:75]
	v_mfma_f32_16x16x32_bf16 v[68:71], v[144:147], v[184:187], v[68:71]
	v_mfma_f32_16x16x32_bf16 v[64:67], v[152:155], v[184:187], v[64:67]
	v_mfma_f32_16x16x32_bf16 v[92:95], v[148:151], v[164:167], v[92:95]
	v_mfma_f32_16x16x32_bf16 v[88:91], v[156:159], v[164:167], v[88:91]
	v_mfma_f32_16x16x32_bf16 v[84:87], v[148:151], v[172:175], v[84:87]
	v_mfma_f32_16x16x32_bf16 v[80:83], v[156:159], v[172:175], v[80:83]
	v_mfma_f32_16x16x32_bf16 v[76:79], v[148:151], v[180:183], v[76:79]
	v_mfma_f32_16x16x32_bf16 v[72:75], v[156:159], v[180:183], v[72:75]
	v_mfma_f32_16x16x32_bf16 v[68:71], v[148:151], v[188:191], v[68:71]
	v_mfma_f32_16x16x32_bf16 v[64:67], v[156:159], v[188:191], v[64:67]
	s_barrier
	s_setprio 0
	s_add_i32 s6, s64, s74
	s_mov_b32 m0, s6
	ds_read_b128 v[160:163], v248 offset:49152
	ds_read_b128 v[164:167], v248 offset:50176
	ds_read_b128 v[168:171], v248 offset:51200
	ds_read_b128 v[172:175], v248 offset:52224
	ds_read_b128 v[176:179], v248 offset:53248
	ds_read_b128 v[180:183], v248 offset:54272
	ds_read_b128 v[184:187], v248 offset:55296
	ds_read_b128 v[188:191], v248 offset:56320
	global_load_lds_dwordx4 v194, s[76:77]
	s_add_i32 m0, s6, 0x2000
	s_add_u32 s6, s76, 0x100000
	s_addc_u32 s7, s77, 0
	s_add_i32 s64, s65, s74
	global_load_lds_dwordx4 v198, s[76:77]
	s_mov_b32 m0, s64
	s_nop 0
	global_load_lds_dwordx4 v194, s[6:7]
	s_add_i32 m0, s64, 0x2000
	s_nop 0
	global_load_lds_dwordx4 v198, s[6:7]
	s_mov_b32 m0, s43
	s_nop 0
	global_load_lds_dwordx4 v192, s[78:79]
	s_mov_b32 m0, s44
	s_nop 0
	global_load_lds_dwordx4 v196, s[78:79]
	s_waitcnt vmcnt(8)
	s_waitcnt lgkmcnt(0)
	s_setprio 1
	s_barrier
	v_mfma_f32_16x16x32_bf16 v[60:63], v[128:131], v[160:163], v[60:63]
	v_mfma_f32_16x16x32_bf16 v[56:59], v[136:139], v[160:163], v[56:59]
	v_mfma_f32_16x16x32_bf16 v[52:55], v[128:131], v[168:171], v[52:55]
	v_mfma_f32_16x16x32_bf16 v[48:51], v[136:139], v[168:171], v[48:51]
	v_mfma_f32_16x16x32_bf16 v[44:47], v[128:131], v[176:179], v[44:47]
	v_mfma_f32_16x16x32_bf16 v[40:43], v[136:139], v[176:179], v[40:43]
	v_mfma_f32_16x16x32_bf16 v[36:39], v[128:131], v[184:187], v[36:39]
	v_mfma_f32_16x16x32_bf16 v[32:35], v[136:139], v[184:187], v[32:35]
	v_mfma_f32_16x16x32_bf16 v[60:63], v[132:135], v[164:167], v[60:63]
	v_mfma_f32_16x16x32_bf16 v[56:59], v[140:143], v[164:167], v[56:59]
	v_mfma_f32_16x16x32_bf16 v[52:55], v[132:135], v[172:175], v[52:55]
	v_mfma_f32_16x16x32_bf16 v[48:51], v[140:143], v[172:175], v[48:51]
	v_mfma_f32_16x16x32_bf16 v[44:47], v[132:135], v[180:183], v[44:47]
	v_mfma_f32_16x16x32_bf16 v[40:43], v[140:143], v[180:183], v[40:43]
	v_mfma_f32_16x16x32_bf16 v[36:39], v[132:135], v[188:191], v[36:39]
	v_mfma_f32_16x16x32_bf16 v[32:35], v[140:143], v[188:191], v[32:35]
	v_mfma_f32_16x16x32_bf16 v[28:31], v[144:147], v[160:163], v[28:31]
	v_mfma_f32_16x16x32_bf16 v[24:27], v[152:155], v[160:163], v[24:27]
	v_mfma_f32_16x16x32_bf16 v[20:23], v[144:147], v[168:171], v[20:23]
	v_mfma_f32_16x16x32_bf16 v[16:19], v[152:155], v[168:171], v[16:19]
	v_mfma_f32_16x16x32_bf16 v[12:15], v[144:147], v[176:179], v[12:15]
	v_mfma_f32_16x16x32_bf16 v[8:11], v[152:155], v[176:179], v[8:11]
	v_mfma_f32_16x16x32_bf16 v[4:7], v[144:147], v[184:187], v[4:7]
	v_mfma_f32_16x16x32_bf16 v[0:3], v[152:155], v[184:187], v[0:3]
	v_mfma_f32_16x16x32_bf16 v[28:31], v[148:151], v[164:167], v[28:31]
	v_mfma_f32_16x16x32_bf16 v[24:27], v[156:159], v[164:167], v[24:27]
	v_mfma_f32_16x16x32_bf16 v[20:23], v[148:151], v[172:175], v[20:23]
	v_mfma_f32_16x16x32_bf16 v[16:19], v[156:159], v[172:175], v[16:19]
	v_mfma_f32_16x16x32_bf16 v[12:15], v[148:151], v[180:183], v[12:15]
	v_mfma_f32_16x16x32_bf16 v[8:11], v[156:159], v[180:183], v[8:11]
	v_mfma_f32_16x16x32_bf16 v[4:7], v[148:151], v[188:191], v[4:7]
	v_mfma_f32_16x16x32_bf16 v[0:3], v[156:159], v[188:191], v[0:3]
	s_barrier
	s_setprio 0
	s_add_i32 vcc_lo, vcc_lo, 2
	s_add_u32 s0, s0, 0x100
	s_addc_u32 s1, s1, 0
	s_cmp_gt_u32 vcc_lo, 61
	s_cbranch_scc0 .LBB0_186
	s_and_b64 vcc, exec, s[80:81]
	s_cbranch_vccz .LBB0_189
	s_barrier

; #define PG8_STAGE(bufoff, gbase, voff) do { _Pragma("unroll") for (int _i = 0; _i < 2; ++_i) \
;         __builtin_amdgcn_global_load_lds((const unsigned*)((const char*)(gbase) + (voff)[_i]), (PG8_LAS unsigned*)(lds + (bufoff) + ldsw + _i * 8192), 16, 0, 0); } while (0)
; #define PG8_LDA(dst, b, h) do { _Pragma("unroll") for (int m = 0; m < 4; ++m) _Pragma("unroll") for (int k = 0; k < 2; ++k) dst[m][k] = *(const PG8_LAS bf16x8*)(lds + PG8_SA(b, h) + aoff + m * 2048 + k * 1024); } while (0)
; #define PG8_LDB(dst, b, h) do { _Pragma("unroll") for (int n = 0; n < 2; ++n) _Pragma("unroll") for (int k = 0; k < 2; ++k) dst[n][k] = *(const PG8_LAS bf16x8*)(lds + PG8_SB(b, h) + boff + n * 2048 + k * 1024); } while (0)
; #define PG8_WAIT_V(n) asm volatile("s_waitcnt vmcnt(" #n ")" ::: "memory")
; #define PG8_WAIT_L(n) asm volatile("s_waitcnt lgkmcnt(" #n ")" ::: "memory")
; #define PG8_BAR __builtin_amdgcn_s_barrier()
; template <class Epi, class Sched, bool ALIGN_EPI = false, bool SP2 = false, bool F8 = false>
; __device__ __forceinline__ void gemm_phase(PG8_LAS unsigned char* lds, const int K, const Sched& S, const Epi& E, const int wave) {
;     ...
;             const bool last = (t == nt - 2);
;             const char* a1 = cA + (size_t)(t + 1) * kstep;
;             const char* a2 = last ? nA : cA + (size_t)(t + 2) * kstep; const char* b2 = last ? nB : cB + (size_t)(t + 2) * kstep;
;             const char* a3 = a2 + kstep; const char* b3 = b2 + kstep;
;             asm volatile("" : "+s"(a1), "+s"(a2), "+s"(b2), "+s"(a3), "+s"(b3));
;             if (last && has_next) S.a_ready(nxt);
;             if constexpr (Epi::KHOOK) { if (cur.prob == 2 ? (t == 16) : (t == 32 || t == 48)) { if (wr == 0) PG8_BAR;
;                 E.khook(acc, cur, (cur.prob == 2 || t == 48) ? 1 : 0, wr, wc, fr, fq); if (wr == 1) PG8_BAR; } }
;             if constexpr (SP2) {
;             PG8_LDB(B0, 0, 0); PG8_LDB(B1, 0, 1); PG8_SCHED; PG8_LDA(At, 0, 0); PG8_STAGE(PG8_SA(1, 1), a1 + hstep, voffA);
;             PG8_WAIT_V(8); PG8_WAIT_L(0); PG8_BAR; PG8_MMA(0, 0, At, B0); PG8_MMA(0, 1, At, B1); PG8_BAR; PG8_SCHED;
;             PG8_LDA(At, 0, 1); PG8_STAGE(PG8_SB(0, 0), b2, voffB); PG8_STAGE(PG8_SB(0, 1), b2 + hstep, voffB); PG8_STAGE(PG8_SA(0, 0), a2, voffA);
;             PG8_WAIT_V(8); PG8_WAIT_L(0); PG8_BAR; PG8_MMA(1, 0, At, B0); PG8_MMA(1, 1, At, B1); PG8_BAR; PG8_SCHED;
.Lpeel_k248:
	v_add_u32_e32 v133, s49, v163
	v_add_u32_e32 v135, s50, v163
	v_add_u32_e32 v161, 0x18000, v163
	v_add_u32_e32 v253, 0x1c000, v163
	s_add_u32 s6, s10, s94
	s_addc_u32 s7, s11, s95
	s_add_u32 s36, s6, 0xffffff80
	s_addc_u32 s37, s7, -1
	s_add_u32 s78, s12, s94
	s_addc_u32 s79, s13, s95
	s_cmp_eq_u32 s38, 28
	s_cselect_b32 s76, s90, s6
	s_cselect_b32 s77, s91, s7
	s_cselect_b32 s7, s93, s79
	s_cselect_b32 s6, s92, s78
	s_add_u32 s96, s76, 0x80
	s_addc_u32 s97, s77, 0
	s_add_u32 s78, s6, 0x80
	s_addc_u32 s79, s7, 0
	ds_read_b128 v[140:143], v133
	ds_read_b128 v[144:147], v133 offset:1024
	ds_read_b128 v[148:151], v133 offset:2048
	ds_read_b128 v[152:155], v133 offset:3072
	ds_read_b128 v[168:171], v135
	ds_read_b128 v[172:175], v135 offset:1024
	ds_read_b128 v[176:179], v135 offset:2048
	ds_read_b128 v[180:183], v135 offset:3072
	s_add_u32 s36, s36, 0x100000
	s_addc_u32 s37, s37, 0
	s_add_i32 m0, s42, 0xc000
	ds_read_b128 v[184:187], v165
	ds_read_b128 v[188:191], v165 offset:1024
	ds_read_b128 v[192:195], v165 offset:2048
	ds_read_b128 v[196:199], v165 offset:3072
	ds_read_b128 v[200:203], v165 offset:4096
	ds_read_b128 v[204:207], v165 offset:5120
	ds_read_b128 v[208:211], v165 offset:6144
	ds_read_b128 v[212:215], v165 offset:7168
	global_load_lds_dwordx4 v134, s[36:37]
	s_add_i32 m0, s42, 0xe000
	s_nop 0
	global_load_lds_dwordx4 v160, s[36:37]
	s_waitcnt vmcnt(8)
	s_waitcnt lgkmcnt(0)
	s_setprio 1
	s_barrier
	v_mfma_scale_f32_16x16x128_f8f6f4 v[124:127], v[140:147], v[184:191], 0, v166, v166 op_sel_hi:[0, 0, 0]
	v_mfma_scale_f32_16x16x128_f8f6f4 v[120:123], v[148:155], v[184:191], 0, v166, v166 op_sel_hi:[0, 0, 0]
	v_mfma_scale_f32_16x16x128_f8f6f4 v[116:119], v[140:147], v[192:199], 0, v166, v166 op_sel_hi:[0, 0, 0]
	v_mfma_scale_f32_16x16x128_f8f6f4 v[112:115], v[148:155], v[192:199], 0, v166, v166 op_sel_hi:[0, 0, 0]
	v_mfma_scale_f32_16x16x128_f8f6f4 v[108:111], v[140:147], v[200:207], 0, v166, v166 op_sel_hi:[0, 0, 0]
	v_mfma_scale_f32_16x16x128_f8f6f4 v[104:107], v[148:155], v[200:207], 0, v166, v166 op_sel_hi:[0, 0, 0]
	v_mfma_scale_f32_16x16x128_f8f6f4 v[100:103], v[140:147], v[208:215], 0, v166, v166 op_sel_hi:[0, 0, 0]
	v_mfma_scale_f32_16x16x128_f8f6f4 v[96:99], v[148:155], v[208:215], 0, v166, v166 op_sel_hi:[0, 0, 0]
	v_mfma_scale_f32_16x16x128_f8f6f4 v[156:159], v[168:175], v[184:191], 0, v166, v166 op_sel_hi:[0, 0, 0]
	v_mfma_scale_f32_16x16x128_f8f6f4 v[184:187], v[176:183], v[184:191], 0, v166, v166 op_sel_hi:[0, 0, 0]
	v_mfma_scale_f32_16x16x128_f8f6f4 v[188:191], v[168:175], v[192:199], 0, v166, v166 op_sel_hi:[0, 0, 0]
	v_mfma_scale_f32_16x16x128_f8f6f4 v[192:195], v[176:183], v[192:199], 0, v166, v166 op_sel_hi:[0, 0, 0]
	v_mfma_scale_f32_16x16x128_f8f6f4 v[196:199], v[168:175], v[200:207], 0, v166, v166 op_sel_hi:[0, 0, 0]
	v_mfma_scale_f32_16x16x128_f8f6f4 v[200:203], v[176:183], v[200:207], 0, v166, v166 op_sel_hi:[0, 0, 0]
	v_mfma_scale_f32_16x16x128_f8f6f4 v[204:207], v[168:175], v[208:215], 0, v166, v166 op_sel_hi:[0, 0, 0]
	v_mfma_scale_f32_16x16x128_f8f6f4 v[208:211], v[176:183], v[208:215], 0, v166, v166 op_sel_hi:[0, 0, 0]
	s_barrier
	s_setprio 0
	s_add_i32 s36, s49, s74
	s_mov_b32 m0, s36
	s_nop 1
	ds_read_b128 v[64:67], v165 offset:16384
	ds_read_b128 v[68:71], v165 offset:17408
	ds_read_b128 v[72:75], v165 offset:18432
	ds_read_b128 v[76:79], v165 offset:19456
	ds_read_b128 v[80:83], v165 offset:20480
	ds_read_b128 v[84:87], v165 offset:21504
	ds_read_b128 v[88:91], v165 offset:22528
	ds_read_b128 v[92:95], v165 offset:23552
	global_load_lds_dwordx4 v132, s[6:7]
	s_add_i32 m0, s36, 0x2000
	s_nop 0
	global_load_lds_dwordx4 v252, s[6:7]
	s_add_u32 s6, s6, 0x100000
	s_addc_u32 s7, s7, 0
	s_add_i32 s36, s50, s74
	s_mov_b32 m0, s36
	s_nop 0
	global_load_lds_dwordx4 v132, s[6:7]
	s_add_i32 m0, s36, 0x2000
	s_nop 0
	global_load_lds_dwordx4 v252, s[6:7]
	s_mov_b32 m0, s42
	s_nop 0
	global_load_lds_dwordx4 v134, s[76:77]
	s_mov_b32 m0, s43
	s_nop 0
	global_load_lds_dwordx4 v160, s[76:77]
	s_waitcnt vmcnt(8)
	s_waitcnt lgkmcnt(0)
	s_setprio 1
	s_barrier
	v_mfma_scale_f32_16x16x128_f8f6f4 v[60:63], v[140:147], v[64:71], 0, v166, v166 op_sel_hi:[0, 0, 0]
	v_mfma_scale_f32_16x16x128_f8f6f4 v[56:59], v[148:155], v[64:71], 0, v166, v166 op_sel_hi:[0, 0, 0]
	v_mfma_scale_f32_16x16x128_f8f6f4 v[52:55], v[140:147], v[72:79], 0, v166, v166 op_sel_hi:[0, 0, 0]
	v_mfma_scale_f32_16x16x128_f8f6f4 v[48:51], v[148:155], v[72:79], 0, v166, v166 op_sel_hi:[0, 0, 0]
	v_mfma_scale_f32_16x16x128_f8f6f4 v[212:215], v[140:147], v[80:87], 0, v166, v166 op_sel_hi:[0, 0, 0]
	v_mfma_scale_f32_16x16x128_f8f6f4 v[216:219], v[148:155], v[80:87], 0, v166, v166 op_sel_hi:[0, 0, 0]
	v_mfma_scale_f32_16x16x128_f8f6f4 v[220:223], v[140:147], v[88:95], 0, v166, v166 op_sel_hi:[0, 0, 0]
	v_mfma_scale_f32_16x16x128_f8f6f4 v[224:227], v[148:155], v[88:95], 0, v166, v166 op_sel_hi:[0, 0, 0]
	v_mfma_scale_f32_16x16x128_f8f6f4 v[228:231], v[168:175], v[64:71], 0, v166, v166 op_sel_hi:[0, 0, 0]
	v_mfma_scale_f32_16x16x128_f8f6f4 v[236:239], v[176:183], v[64:71], 0, v166, v166 op_sel_hi:[0, 0, 0]
	v_mfma_scale_f32_16x16x128_f8f6f4 v[244:247], v[168:175], v[72:79], 0, v166, v166 op_sel_hi:[0, 0, 0]
	v_mfma_scale_f32_16x16x128_f8f6f4 v[248:251], v[176:183], v[72:79], 0, v166, v166 op_sel_hi:[0, 0, 0]
	v_mfma_scale_f32_16x16x128_f8f6f4 v[232:235], v[168:175], v[80:87], 0, v166, v166 op_sel_hi:[0, 0, 0]
	v_mfma_scale_f32_16x16x128_f8f6f4 v[240:243], v[176:183], v[80:87], 0, v166, v166 op_sel_hi:[0, 0, 0]
	v_mfma_scale_f32_16x16x128_f8f6f4 v[136:139], v[168:175], v[88:95], 0, v166, v166 op_sel_hi:[0, 0, 0]
	v_mfma_scale_f32_16x16x128_f8f6f4 v[128:131], v[176:183], v[88:95], 0, v166, v166 op_sel_hi:[0, 0, 0]
	s_barrier
	s_branch .Lmid_k248
; #define PG8_STAGE(bufoff, gbase, voff) do { _Pragma("unroll") for (int _i = 0; _i < 2; ++_i) \
;         __builtin_amdgcn_global_load_lds((const unsigned*)((const char*)(gbase) + (voff)[_i]), (PG8_LAS unsigned*)(lds + (bufoff) + ldsw + _i * 8192), 16, 0, 0); } while (0)
; #define PG8_LDA(dst, b, h) do { _Pragma("unroll") for (int m = 0; m < 4; ++m) _Pragma("unroll") for (int k = 0; k < 2; ++k) dst[m][k] = *(const PG8_LAS bf16x8*)(lds + PG8_SA(b, h) + aoff + m * 2048 + k * 1024); } while (0)
; #define PG8_LDB(dst, b, h) do { _Pragma("unroll") for (int n = 0; n < 2; ++n) _Pragma("unroll") for (int k = 0; k < 2; ++k) dst[n][k] = *(const PG8_LAS bf16x8*)(lds + PG8_SB(b, h) + boff + n * 2048 + k * 1024); } while (0)
; #define PG8_WAIT_V(n) asm volatile("s_waitcnt vmcnt(" #n ")" ::: "memory")
; #define PG8_WAIT_L(n) asm volatile("s_waitcnt lgkmcnt(" #n ")" ::: "memory")
; #define PG8_BAR __builtin_amdgcn_s_barrier()
; template <class Epi, class Sched, bool ALIGN_EPI = false, bool SP2 = false, bool F8 = false>
; __device__ __forceinline__ void gemm_phase(PG8_LAS unsigned char* lds, const int K, const Sched& S, const Epi& E, const int wave) {
;     ...
;             const bool last = (t == nt - 2);
;             const char* a1 = cA + (size_t)(t + 1) * kstep;
;             const char* a2 = last ? nA : cA + (size_t)(t + 2) * kstep; const char* b2 = last ? nB : cB + (size_t)(t + 2) * kstep;
;             const char* a3 = a2 + kstep; const char* b3 = b2 + kstep;
;             asm volatile("" : "+s"(a1), "+s"(a2), "+s"(b2), "+s"(a3), "+s"(b3));
;             if (last && has_next) S.a_ready(nxt);
;             if constexpr (Epi::KHOOK) { if (cur.prob == 2 ? (t == 16) : (t == 32 || t == 48)) { if (wr == 0) PG8_BAR;
;                 E.khook(acc, cur, (cur.prob == 2 || t == 48) ? 1 : 0, wr, wc, fr, fq); if (wr == 1) PG8_BAR; } }
;             if constexpr (SP2) {
;             PG8_LDB(B0, 0, 0); PG8_LDB(B1, 0, 1); PG8_SCHED; PG8_LDA(At, 0, 0); PG8_STAGE(PG8_SA(1, 1), a1 + hstep, voffA);
;             PG8_WAIT_V(8); PG8_WAIT_L(0); PG8_BAR; PG8_MMA(0, 0, At, B0); PG8_MMA(0, 1, At, B1); PG8_BAR; PG8_SCHED;
;             PG8_LDA(At, 0, 1); PG8_STAGE(PG8_SB(0, 0), b2, voffB); PG8_STAGE(PG8_SB(0, 1), b2 + hstep, voffB); PG8_STAGE(PG8_SA(0, 0), a2, voffA);
;             PG8_WAIT_V(8); PG8_WAIT_L(0); PG8_BAR; PG8_MMA(1, 0, At, B0); PG8_MMA(1, 1, At, B1); PG8_BAR; PG8_SCHED;
.LBB0_248:
	s_add_u32 s6, s10, s94
	s_addc_u32 s7, s11, s95
	s_add_u32 s36, s6, 0xffffff80
	s_addc_u32 s37, s7, -1
	s_add_u32 s78, s12, s94
	s_addc_u32 s79, s13, s95
	s_cmp_eq_u32 s38, 28
	s_cselect_b32 s76, s90, s6
	s_cselect_b32 s77, s91, s7
	s_cselect_b32 s7, s93, s79
	s_cselect_b32 s6, s92, s78
	s_add_u32 s96, s76, 0x80
	s_addc_u32 s97, s77, 0
	s_add_u32 s78, s6, 0x80
	s_addc_u32 s79, s7, 0
	ds_read_b128 v[140:143], v133
	ds_read_b128 v[144:147], v133 offset:1024
	ds_read_b128 v[148:151], v133 offset:2048
	ds_read_b128 v[152:155], v133 offset:3072
	ds_read_b128 v[168:171], v135
	ds_read_b128 v[172:175], v135 offset:1024
	ds_read_b128 v[176:179], v135 offset:2048
	ds_read_b128 v[180:183], v135 offset:3072
	s_add_u32 s36, s36, 0x100000
	s_addc_u32 s37, s37, 0
	s_add_i32 m0, s42, 0xc000
	ds_read_b128 v[184:187], v165
	ds_read_b128 v[188:191], v165 offset:1024
	ds_read_b128 v[192:195], v165 offset:2048
	ds_read_b128 v[196:199], v165 offset:3072
	ds_read_b128 v[200:203], v165 offset:4096
	ds_read_b128 v[204:207], v165 offset:5120
	ds_read_b128 v[208:211], v165 offset:6144
	ds_read_b128 v[212:215], v165 offset:7168
	global_load_lds_dwordx4 v134, s[36:37]
	s_add_i32 m0, s42, 0xe000
	s_nop 0
	global_load_lds_dwordx4 v160, s[36:37]
	s_waitcnt vmcnt(8)
	s_waitcnt lgkmcnt(0)
	s_setprio 1
	s_barrier
	v_mfma_scale_f32_16x16x128_f8f6f4 v[124:127], v[140:147], v[184:191], v[124:127], v166, v166 op_sel_hi:[0,0,0]
	v_mfma_scale_f32_16x16x128_f8f6f4 v[120:123], v[148:155], v[184:191], v[120:123], v166, v166 op_sel_hi:[0,0,0]
	v_mfma_scale_f32_16x16x128_f8f6f4 v[116:119], v[140:147], v[192:199], v[116:119], v166, v166 op_sel_hi:[0,0,0]
	v_mfma_scale_f32_16x16x128_f8f6f4 v[112:115], v[148:155], v[192:199], v[112:115], v166, v166 op_sel_hi:[0,0,0]
	v_mfma_scale_f32_16x16x128_f8f6f4 v[108:111], v[140:147], v[200:207], v[108:111], v166, v166 op_sel_hi:[0,0,0]
	v_mfma_scale_f32_16x16x128_f8f6f4 v[104:107], v[148:155], v[200:207], v[104:107], v166, v166 op_sel_hi:[0,0,0]
	v_mfma_scale_f32_16x16x128_f8f6f4 v[100:103], v[140:147], v[208:215], v[100:103], v166, v166 op_sel_hi:[0,0,0]
	v_mfma_scale_f32_16x16x128_f8f6f4 v[96:99], v[148:155], v[208:215], v[96:99], v166, v166 op_sel_hi:[0,0,0]
	v_mfma_scale_f32_16x16x128_f8f6f4 v[156:159], v[168:175], v[184:191], v[92:95], v166, v166 op_sel_hi:[0,0,0]
	v_mfma_scale_f32_16x16x128_f8f6f4 v[184:187], v[176:183], v[184:191], v[88:91], v166, v166 op_sel_hi:[0,0,0]
	v_mfma_scale_f32_16x16x128_f8f6f4 v[188:191], v[168:175], v[192:199], v[84:87], v166, v166 op_sel_hi:[0,0,0]
	v_mfma_scale_f32_16x16x128_f8f6f4 v[192:195], v[176:183], v[192:199], v[80:83], v166, v166 op_sel_hi:[0,0,0]
	v_mfma_scale_f32_16x16x128_f8f6f4 v[196:199], v[168:175], v[200:207], v[76:79], v166, v166 op_sel_hi:[0,0,0]
	v_mfma_scale_f32_16x16x128_f8f6f4 v[200:203], v[176:183], v[200:207], v[72:75], v166, v166 op_sel_hi:[0,0,0]
	v_mfma_scale_f32_16x16x128_f8f6f4 v[204:207], v[168:175], v[208:215], v[68:71], v166, v166 op_sel_hi:[0,0,0]
	v_mfma_scale_f32_16x16x128_f8f6f4 v[208:211], v[176:183], v[208:215], v[64:67], v166, v166 op_sel_hi:[0,0,0]
	s_barrier
	s_setprio 0
	s_add_i32 s36, s49, s74
	s_mov_b32 m0, s36
	s_nop 1
	ds_read_b128 v[64:67], v165 offset:16384
	ds_read_b128 v[68:71], v165 offset:17408
	ds_read_b128 v[72:75], v165 offset:18432
	ds_read_b128 v[76:79], v165 offset:19456
	ds_read_b128 v[80:83], v165 offset:20480
	ds_read_b128 v[84:87], v165 offset:21504
	ds_read_b128 v[88:91], v165 offset:22528
	ds_read_b128 v[92:95], v165 offset:23552
	global_load_lds_dwordx4 v132, s[6:7]
	s_add_i32 m0, s36, 0x2000
	s_nop 0
	global_load_lds_dwordx4 v252, s[6:7]
	s_add_u32 s6, s6, 0x100000
	s_addc_u32 s7, s7, 0
	s_add_i32 s36, s50, s74
	s_mov_b32 m0, s36
	s_nop 0
	global_load_lds_dwordx4 v132, s[6:7]
	s_add_i32 m0, s36, 0x2000
	s_nop 0
	global_load_lds_dwordx4 v252, s[6:7]
	s_mov_b32 m0, s42
	s_nop 0
	global_load_lds_dwordx4 v134, s[76:77]
	s_mov_b32 m0, s43
	s_nop 0
	global_load_lds_dwordx4 v160, s[76:77]
	s_waitcnt vmcnt(8)
	s_waitcnt lgkmcnt(0)
	s_setprio 1
	s_barrier
	v_mfma_scale_f32_16x16x128_f8f6f4 v[60:63], v[140:147], v[64:71], v[60:63], v166, v166 op_sel_hi:[0,0,0]
	v_mfma_scale_f32_16x16x128_f8f6f4 v[56:59], v[148:155], v[64:71], v[56:59], v166, v166 op_sel_hi:[0,0,0]
	v_mfma_scale_f32_16x16x128_f8f6f4 v[52:55], v[140:147], v[72:79], v[52:55], v166, v166 op_sel_hi:[0,0,0]
	v_mfma_scale_f32_16x16x128_f8f6f4 v[48:51], v[148:155], v[72:79], v[48:51], v166, v166 op_sel_hi:[0,0,0]
	v_mfma_scale_f32_16x16x128_f8f6f4 v[212:215], v[140:147], v[80:87], v[44:47], v166, v166 op_sel_hi:[0,0,0]
	v_mfma_scale_f32_16x16x128_f8f6f4 v[216:219], v[148:155], v[80:87], v[40:43], v166, v166 op_sel_hi:[0,0,0]
	v_mfma_scale_f32_16x16x128_f8f6f4 v[220:223], v[140:147], v[88:95], v[36:39], v166, v166 op_sel_hi:[0,0,0]
	v_mfma_scale_f32_16x16x128_f8f6f4 v[224:227], v[148:155], v[88:95], v[32:35], v166, v166 op_sel_hi:[0,0,0]
	v_mfma_scale_f32_16x16x128_f8f6f4 v[228:231], v[168:175], v[64:71], v[28:31], v166, v166 op_sel_hi:[0,0,0]
	v_mfma_scale_f32_16x16x128_f8f6f4 v[236:239], v[176:183], v[64:71], v[24:27], v166, v166 op_sel_hi:[0,0,0]
	v_mfma_scale_f32_16x16x128_f8f6f4 v[244:247], v[168:175], v[72:79], v[20:23], v166, v166 op_sel_hi:[0,0,0]
	v_mfma_scale_f32_16x16x128_f8f6f4 v[248:251], v[176:183], v[72:79], v[16:19], v166, v166 op_sel_hi:[0,0,0]
	v_mfma_scale_f32_16x16x128_f8f6f4 v[232:235], v[168:175], v[80:87], v[12:15], v166, v166 op_sel_hi:[0,0,0]
	v_mfma_scale_f32_16x16x128_f8f6f4 v[240:243], v[176:183], v[80:87], v[8:11], v166, v166 op_sel_hi:[0,0,0]
	v_mfma_scale_f32_16x16x128_f8f6f4 v[136:139], v[168:175], v[88:95], v[4:7], v166, v166 op_sel_hi:[0,0,0]
	v_mfma_scale_f32_16x16x128_f8f6f4 v[128:131], v[176:183], v[88:95], v[0:3], v166, v166 op_sel_hi:[0,0,0]
	s_barrier
; #define PG8_STAGE(bufoff, gbase, voff) do { _Pragma("unroll") for (int _i = 0; _i < 2; ++_i) \
;         __builtin_amdgcn_global_load_lds((const unsigned*)((const char*)(gbase) + (voff)[_i]), (PG8_LAS unsigned*)(lds + (bufoff) + ldsw + _i * 8192), 16, 0, 0); } while (0)
; #define PG8_LDA(dst, b, h) do { _Pragma("unroll") for (int m = 0; m < 4; ++m) _Pragma("unroll") for (int k = 0; k < 2; ++k) dst[m][k] = *(const PG8_LAS bf16x8*)(lds + PG8_SA(b, h) + aoff + m * 2048 + k * 1024); } while (0)
; #define PG8_LDB(dst, b, h) do { _Pragma("unroll") for (int n = 0; n < 2; ++n) _Pragma("unroll") for (int k = 0; k < 2; ++k) dst[n][k] = *(const PG8_LAS bf16x8*)(lds + PG8_SB(b, h) + boff + n * 2048 + k * 1024); } while (0)
; #define PG8_WAIT_V(n) asm volatile("s_waitcnt vmcnt(" #n ")" ::: "memory")
; #define PG8_WAIT_L(n) asm volatile("s_waitcnt lgkmcnt(" #n ")" ::: "memory")
; #define PG8_BAR __builtin_amdgcn_s_barrier()
; #define PG8_SCHED __builtin_amdgcn_sched_barrier(0)
; template <class Epi, class Sched, bool ALIGN_EPI = false, bool SP2 = false, bool F8 = false>
; __device__ __forceinline__ void gemm_phase(PG8_LAS unsigned char* lds, const int K, const Sched& S, const Epi& E, const int wave) {
;     ...
;             PG8_LDB(B0, 1, 0); PG8_LDB(B1, 1, 1); PG8_SCHED; PG8_LDA(At, 1, 0); PG8_STAGE(PG8_SA(0, 1), a2 + hstep, voffA);
;             PG8_WAIT_V(8); PG8_WAIT_L(0); PG8_BAR; PG8_MMA(0, 0, At, B0); PG8_MMA(0, 1, At, B1); PG8_BAR; PG8_SCHED;
;             PG8_LDA(At, 1, 1); PG8_STAGE(PG8_SB(1, 0), b3, voffB); PG8_STAGE(PG8_SB(1, 1), b3 + hstep, voffB); PG8_STAGE(PG8_SA(1, 0), a3, voffA);
;             PG8_WAIT_V(8); PG8_WAIT_L(0); PG8_BAR; PG8_MMA(1, 0, At, B0); PG8_MMA(1, 1, At, B1); PG8_BAR; PG8_SCHED;
.Lmid_k248:
	s_setprio 0
	s_add_i32 s36, 0, 0x18000
	s_add_i32 s37, 0, 0x1c000
	s_nop 0
	ds_read_b128 v[0:3], v161
	ds_read_b128 v[4:7], v161 offset:1024
	ds_read_b128 v[8:11], v161 offset:2048
	ds_read_b128 v[12:15], v161 offset:3072
	ds_read_b128 v[140:143], v253
	ds_read_b128 v[144:147], v253 offset:1024
	ds_read_b128 v[148:151], v253 offset:2048
	ds_read_b128 v[152:155], v253 offset:3072
	s_add_u32 s6, s76, 0x100000
	s_addc_u32 s7, s77, 0
	s_mov_b32 m0, s44
	ds_read_b128 v[16:19], v165 offset:32768
	ds_read_b128 v[20:23], v165 offset:33792
	ds_read_b128 v[24:27], v165 offset:34816
	ds_read_b128 v[28:31], v165 offset:35840
	ds_read_b128 v[32:35], v165 offset:36864
	ds_read_b128 v[36:39], v165 offset:37888
	ds_read_b128 v[40:43], v165 offset:38912
	ds_read_b128 v[44:47], v165 offset:39936
	global_load_lds_dwordx4 v134, s[6:7]
	s_mov_b32 m0, s45
	s_nop 0
	global_load_lds_dwordx4 v160, s[6:7]
	s_waitcnt vmcnt(8)
	s_waitcnt lgkmcnt(0)
	s_setprio 1
	s_barrier
	v_mfma_scale_f32_16x16x128_f8f6f4 v[124:127], v[0:7], v[16:23], v[124:127], v166, v166 op_sel_hi:[0,0,0]
	v_mfma_scale_f32_16x16x128_f8f6f4 v[120:123], v[8:15], v[16:23], v[120:123], v166, v166 op_sel_hi:[0,0,0]
	v_mfma_scale_f32_16x16x128_f8f6f4 v[116:119], v[0:7], v[24:31], v[116:119], v166, v166 op_sel_hi:[0,0,0]
	v_mfma_scale_f32_16x16x128_f8f6f4 v[112:115], v[8:15], v[24:31], v[112:115], v166, v166 op_sel_hi:[0,0,0]
	v_mfma_scale_f32_16x16x128_f8f6f4 v[108:111], v[0:7], v[32:39], v[108:111], v166, v166 op_sel_hi:[0,0,0]
	v_mfma_scale_f32_16x16x128_f8f6f4 v[104:107], v[8:15], v[32:39], v[104:107], v166, v166 op_sel_hi:[0,0,0]
	v_mfma_scale_f32_16x16x128_f8f6f4 v[100:103], v[0:7], v[40:47], v[100:103], v166, v166 op_sel_hi:[0,0,0]
	v_mfma_scale_f32_16x16x128_f8f6f4 v[96:99], v[8:15], v[40:47], v[96:99], v166, v166 op_sel_hi:[0,0,0]
	v_mfma_scale_f32_16x16x128_f8f6f4 v[92:95], v[140:147], v[16:23], v[156:159], v166, v166 op_sel_hi:[0,0,0]
	v_mfma_scale_f32_16x16x128_f8f6f4 v[88:91], v[148:155], v[16:23], v[184:187], v166, v166 op_sel_hi:[0,0,0]
	v_mfma_scale_f32_16x16x128_f8f6f4 v[84:87], v[140:147], v[24:31], v[188:191], v166, v166 op_sel_hi:[0,0,0]
	v_mfma_scale_f32_16x16x128_f8f6f4 v[80:83], v[148:155], v[24:31], v[192:195], v166, v166 op_sel_hi:[0,0,0]
	v_mfma_scale_f32_16x16x128_f8f6f4 v[76:79], v[140:147], v[32:39], v[196:199], v166, v166 op_sel_hi:[0,0,0]
	v_mfma_scale_f32_16x16x128_f8f6f4 v[72:75], v[148:155], v[32:39], v[200:203], v166, v166 op_sel_hi:[0,0,0]
	v_mfma_scale_f32_16x16x128_f8f6f4 v[68:71], v[140:147], v[40:47], v[204:207], v166, v166 op_sel_hi:[0,0,0]
	v_mfma_scale_f32_16x16x128_f8f6f4 v[64:67], v[148:155], v[40:47], v[208:211], v166, v166 op_sel_hi:[0,0,0]
	s_barrier
	s_setprio 0
	s_add_i32 s6, s36, s74
	s_mov_b32 m0, s6
	ds_read_b128 v[16:19], v165 offset:49152
	ds_read_b128 v[20:23], v165 offset:50176
	ds_read_b128 v[168:171], v165 offset:51200
	ds_read_b128 v[172:175], v165 offset:52224
	ds_read_b128 v[176:179], v165 offset:53248
	ds_read_b128 v[180:183], v165 offset:54272
	ds_read_b128 v[184:187], v165 offset:55296
	ds_read_b128 v[188:191], v165 offset:56320
	global_load_lds_dwordx4 v132, s[78:79]
	s_add_i32 m0, s6, 0x2000
	s_add_u32 s6, s78, 0x100000
	s_addc_u32 s7, s79, 0
	s_add_i32 s36, s37, s74
	global_load_lds_dwordx4 v252, s[78:79]
	s_mov_b32 m0, s36
	s_nop 0
	global_load_lds_dwordx4 v132, s[6:7]
	s_add_i32 m0, s36, 0x2000
	s_nop 0
	global_load_lds_dwordx4 v252, s[6:7]
	s_mov_b32 m0, s46
	s_nop 0
	global_load_lds_dwordx4 v134, s[96:97]
	s_mov_b32 m0, s47
	s_nop 0
	global_load_lds_dwordx4 v160, s[96:97]
	s_waitcnt vmcnt(8)
	s_waitcnt lgkmcnt(0)
	s_setprio 1
	s_barrier
	v_mfma_scale_f32_16x16x128_f8f6f4 v[60:63], v[0:7], v[16:23], v[60:63], v166, v166 op_sel_hi:[0,0,0]
	v_mfma_scale_f32_16x16x128_f8f6f4 v[56:59], v[8:15], v[16:23], v[56:59], v166, v166 op_sel_hi:[0,0,0]
	v_mfma_scale_f32_16x16x128_f8f6f4 v[52:55], v[0:7], v[168:175], v[52:55], v166, v166 op_sel_hi:[0,0,0]
	v_mfma_scale_f32_16x16x128_f8f6f4 v[48:51], v[8:15], v[168:175], v[48:51], v166, v166 op_sel_hi:[0,0,0]
	v_mfma_scale_f32_16x16x128_f8f6f4 v[44:47], v[0:7], v[176:183], v[212:215], v166, v166 op_sel_hi:[0,0,0]
	v_mfma_scale_f32_16x16x128_f8f6f4 v[40:43], v[8:15], v[176:183], v[216:219], v166, v166 op_sel_hi:[0,0,0]
	v_mfma_scale_f32_16x16x128_f8f6f4 v[36:39], v[0:7], v[184:191], v[220:223], v166, v166 op_sel_hi:[0,0,0]
	v_mfma_scale_f32_16x16x128_f8f6f4 v[32:35], v[8:15], v[184:191], v[224:227], v166, v166 op_sel_hi:[0,0,0]
	v_mfma_scale_f32_16x16x128_f8f6f4 v[28:31], v[140:147], v[16:23], v[228:231], v166, v166 op_sel_hi:[0,0,0]
	v_mfma_scale_f32_16x16x128_f8f6f4 v[24:27], v[148:155], v[16:23], v[236:239], v166, v166 op_sel_hi:[0,0,0]
	v_mfma_scale_f32_16x16x128_f8f6f4 v[20:23], v[140:147], v[168:175], v[244:247], v166, v166 op_sel_hi:[0,0,0]
	v_mfma_scale_f32_16x16x128_f8f6f4 v[16:19], v[148:155], v[168:175], v[248:251], v166, v166 op_sel_hi:[0,0,0]
	v_mfma_scale_f32_16x16x128_f8f6f4 v[12:15], v[140:147], v[176:183], v[232:235], v166, v166 op_sel_hi:[0,0,0]
	v_mfma_scale_f32_16x16x128_f8f6f4 v[8:11], v[148:155], v[176:183], v[240:243], v166, v166 op_sel_hi:[0,0,0]
	v_mfma_scale_f32_16x16x128_f8f6f4 v[4:7], v[140:147], v[184:191], v[136:139], v166, v166 op_sel_hi:[0,0,0]
	v_mfma_scale_f32_16x16x128_f8f6f4 v[0:3], v[148:155], v[184:191], v[128:131], v166, v166 op_sel_hi:[0,0,0]
	s_barrier
	s_setprio 0
	s_add_i32 s38, s38, 2
	s_add_u32 s94, s94, 0x100
	s_addc_u32 s95, s95, 0
	s_cmp_gt_u32 s38, 29
	s_cbranch_scc0 .LBB0_248
	s_and_b64 vcc, exec, s[60:61]
	s_cbranch_vccz .LBB0_251
	s_barrier

; #define PG8_STAGE(bufoff, gbase, voff) do { _Pragma("unroll") for (int _i = 0; _i < 2; ++_i) \
;         __builtin_amdgcn_global_load_lds((const unsigned*)((const char*)(gbase) + (voff)[_i]), (PG8_LAS unsigned*)(lds + (bufoff) + ldsw + _i * 8192), 16, 0, 0); } while (0)
; #define PG8_LDA(dst, b, h) do { _Pragma("unroll") for (int m = 0; m < 4; ++m) _Pragma("unroll") for (int k = 0; k < 2; ++k) dst[m][k] = *(const PG8_LAS bf16x8*)(lds + PG8_SA(b, h) + aoff + m * 2048 + k * 1024); } while (0)
; #define PG8_LDB(dst, b, h) do { _Pragma("unroll") for (int n = 0; n < 2; ++n) _Pragma("unroll") for (int k = 0; k < 2; ++k) dst[n][k] = *(const PG8_LAS bf16x8*)(lds + PG8_SB(b, h) + boff + n * 2048 + k * 1024); } while (0)
; #define PG8_WAIT_V(n) asm volatile("s_waitcnt vmcnt(" #n ")" ::: "memory")
; #define PG8_WAIT_L(n) asm volatile("s_waitcnt lgkmcnt(" #n ")" ::: "memory")
; #define PG8_BAR __builtin_amdgcn_s_barrier()
; template <class Epi, class Sched, bool ALIGN_EPI = false, bool SP2 = false, bool F8 = false>
; __device__ __forceinline__ void gemm_phase(PG8_LAS unsigned char* lds, const int K, const Sched& S, const Epi& E, const int wave) {
;     ...
;             const bool last = (t == nt - 2);
;             const char* a1 = cA + (size_t)(t + 1) * kstep;
;             const char* a2 = last ? nA : cA + (size_t)(t + 2) * kstep; const char* b2 = last ? nB : cB + (size_t)(t + 2) * kstep;
;             const char* a3 = a2 + kstep; const char* b3 = b2 + kstep;
;             asm volatile("" : "+s"(a1), "+s"(a2), "+s"(b2), "+s"(a3), "+s"(b3));
;             if (last && has_next) S.a_ready(nxt);
;             if constexpr (Epi::KHOOK) { if (cur.prob == 2 ? (t == 16) : (t == 32 || t == 48)) { if (wr == 0) PG8_BAR;
;                 E.khook(acc, cur, (cur.prob == 2 || t == 48) ? 1 : 0, wr, wc, fr, fq); if (wr == 1) PG8_BAR; } }
;             if constexpr (SP2) {
;             PG8_LDB(B0, 0, 0); PG8_LDB(B1, 0, 1); PG8_SCHED; PG8_LDA(At, 0, 0); PG8_STAGE(PG8_SA(1, 1), a1 + hstep, voffA);
;             PG8_WAIT_V(8); PG8_WAIT_L(0); PG8_BAR; PG8_MMA(0, 0, At, B0); PG8_MMA(0, 1, At, B1); PG8_BAR; PG8_SCHED;
;             PG8_LDA(At, 0, 1); PG8_STAGE(PG8_SB(0, 0), b2, voffB); PG8_STAGE(PG8_SB(0, 1), b2 + hstep, voffB); PG8_STAGE(PG8_SA(0, 0), a2, voffA);
;             PG8_WAIT_V(8); PG8_WAIT_L(0); PG8_BAR; PG8_MMA(1, 0, At, B0); PG8_MMA(1, 1, At, B1); PG8_BAR; PG8_SCHED;
.Lpeel_k966:
	v_add_u32_e32 v220, s77, v168
	v_add_u32_e32 v221, s78, v168
	v_add_u32_e32 v222, 0x18000, v168
	v_add_u32_e32 v223, 0x1c000, v168
	s_add_i32 s90, s8, 2
	s_cmp_eq_u32 s85, s8
	s_cselect_b32 s42, s31, s86
	s_cselect_b32 s43, s25, s87
	s_cselect_b32 s57, s83, s89
	s_cselect_b32 s56, s84, s88
	s_add_u32 s8, s42, 0x80
	s_addc_u32 s9, s43, 0
	s_add_u32 s40, s56, 0x80
	s_addc_u32 s41, s57, 0
	s_mov_b64 s[92:93], s[6:7]
	ds_read_b128 v[132:135], v220
	ds_read_b128 v[136:139], v220 offset:1024
	ds_read_b128 v[156:159], v220 offset:2048
	ds_read_b128 v[160:163], v220 offset:3072
	ds_read_b128 v[172:175], v221
	ds_read_b128 v[176:179], v221 offset:1024
	ds_read_b128 v[180:183], v221 offset:2048
	ds_read_b128 v[184:187], v221 offset:3072
	s_add_u32 s92, s92, 0x100000
	s_addc_u32 s93, s93, 0
	s_add_i32 m0, s64, 0xc000
	ds_read_b128 v[188:191], v170
	ds_read_b128 v[192:195], v170 offset:1024
	ds_read_b128 v[196:199], v170 offset:2048
	ds_read_b128 v[200:203], v170 offset:3072
	ds_read_b128 v[204:207], v170 offset:4096
	ds_read_b128 v[208:211], v170 offset:5120
	ds_read_b128 v[212:215], v170 offset:6144
	ds_read_b128 v[216:219], v170 offset:7168
	global_load_lds_dwordx4 v140, s[92:93]
	s_add_i32 m0, s64, 0xe000
	s_nop 0
	global_load_lds_dwordx4 v144, s[92:93]
	s_waitcnt vmcnt(8)
	s_waitcnt lgkmcnt(0)
	s_setprio 1
	s_barrier
	v_mfma_f32_16x16x32_bf16 v[128:131], v[132:135], v[188:191], 0
	v_mfma_f32_16x16x32_bf16 v[124:127], v[156:159], v[188:191], 0
	v_mfma_f32_16x16x32_bf16 v[120:123], v[132:135], v[196:199], 0
	v_mfma_f32_16x16x32_bf16 v[116:119], v[156:159], v[196:199], 0
	v_mfma_f32_16x16x32_bf16 v[112:115], v[132:135], v[204:207], 0
	v_mfma_f32_16x16x32_bf16 v[108:111], v[156:159], v[204:207], 0
	v_mfma_f32_16x16x32_bf16 v[104:107], v[132:135], v[212:215], 0
	v_mfma_f32_16x16x32_bf16 v[100:103], v[156:159], v[212:215], 0
	v_mfma_f32_16x16x32_bf16 v[128:131], v[136:139], v[192:195], v[128:131]
	v_mfma_f32_16x16x32_bf16 v[124:127], v[160:163], v[192:195], v[124:127]
	v_mfma_f32_16x16x32_bf16 v[120:123], v[136:139], v[200:203], v[120:123]
	v_mfma_f32_16x16x32_bf16 v[116:119], v[160:163], v[200:203], v[116:119]
	v_mfma_f32_16x16x32_bf16 v[112:115], v[136:139], v[208:211], v[112:115]
	v_mfma_f32_16x16x32_bf16 v[108:111], v[160:163], v[208:211], v[108:111]
	v_mfma_f32_16x16x32_bf16 v[104:107], v[136:139], v[216:219], v[104:107]
	v_mfma_f32_16x16x32_bf16 v[100:103], v[160:163], v[216:219], v[100:103]
	v_mfma_f32_16x16x32_bf16 v[96:99], v[172:175], v[188:191], 0
	v_mfma_f32_16x16x32_bf16 v[92:95], v[180:183], v[188:191], 0
	v_mfma_f32_16x16x32_bf16 v[88:91], v[172:175], v[196:199], 0
	v_mfma_f32_16x16x32_bf16 v[84:87], v[180:183], v[196:199], 0
	v_mfma_f32_16x16x32_bf16 v[80:83], v[172:175], v[204:207], 0
	v_mfma_f32_16x16x32_bf16 v[76:79], v[180:183], v[204:207], 0
	v_mfma_f32_16x16x32_bf16 v[72:75], v[172:175], v[212:215], 0
	v_mfma_f32_16x16x32_bf16 v[68:71], v[180:183], v[212:215], 0
	v_mfma_f32_16x16x32_bf16 v[96:99], v[176:179], v[192:195], v[96:99]
	v_mfma_f32_16x16x32_bf16 v[92:95], v[184:187], v[192:195], v[92:95]
	v_mfma_f32_16x16x32_bf16 v[88:91], v[176:179], v[200:203], v[88:91]
	v_mfma_f32_16x16x32_bf16 v[84:87], v[184:187], v[200:203], v[84:87]
	v_mfma_f32_16x16x32_bf16 v[80:83], v[176:179], v[208:211], v[80:83]
	v_mfma_f32_16x16x32_bf16 v[76:79], v[184:187], v[208:211], v[76:79]
	v_mfma_f32_16x16x32_bf16 v[72:75], v[176:179], v[216:219], v[72:75]
	v_mfma_f32_16x16x32_bf16 v[68:71], v[184:187], v[216:219], v[68:71]
	s_barrier
	s_setprio 0
	s_add_i32 s91, s77, s63
	s_mov_b32 m0, s91
	ds_read_b128 v[188:191], v170 offset:16384
	ds_read_b128 v[192:195], v170 offset:17408
	ds_read_b128 v[196:199], v170 offset:18432
	ds_read_b128 v[200:203], v170 offset:19456
	ds_read_b128 v[204:207], v170 offset:20480
	ds_read_b128 v[208:211], v170 offset:21504
	ds_read_b128 v[212:215], v170 offset:22528
	ds_read_b128 v[216:219], v170 offset:23552
	global_load_lds_dwordx4 v142, s[56:57]
	s_add_i32 m0, s91, 0x2000
	s_nop 0
	global_load_lds_dwordx4 v146, s[56:57]
	s_add_u32 s56, s56, 0x100000
	s_addc_u32 s57, s57, 0
	s_add_i32 s91, s78, s63
	s_mov_b32 m0, s91
	s_nop 0
	global_load_lds_dwordx4 v142, s[56:57]
	s_add_i32 m0, s91, 0x2000
	s_nop 0
	global_load_lds_dwordx4 v146, s[56:57]
	s_mov_b32 m0, s64
	s_nop 0
	global_load_lds_dwordx4 v140, s[42:43]
	s_mov_b32 m0, s65
	s_nop 0
	global_load_lds_dwordx4 v144, s[42:43]
	s_waitcnt vmcnt(8)
	s_waitcnt lgkmcnt(0)
	s_setprio 1
	s_barrier
	v_mfma_f32_16x16x32_bf16 v[64:67], v[132:135], v[188:191], 0
	v_mfma_f32_16x16x32_bf16 v[60:63], v[156:159], v[188:191], 0
	v_mfma_f32_16x16x32_bf16 v[56:59], v[132:135], v[196:199], 0
	v_mfma_f32_16x16x32_bf16 v[52:55], v[156:159], v[196:199], 0
	v_mfma_f32_16x16x32_bf16 v[48:51], v[132:135], v[204:207], 0
	v_mfma_f32_16x16x32_bf16 v[44:47], v[156:159], v[204:207], 0
	v_mfma_f32_16x16x32_bf16 v[40:43], v[132:135], v[212:215], 0
	v_mfma_f32_16x16x32_bf16 v[36:39], v[156:159], v[212:215], 0
	v_mfma_f32_16x16x32_bf16 v[64:67], v[136:139], v[192:195], v[64:67]
	v_mfma_f32_16x16x32_bf16 v[60:63], v[160:163], v[192:195], v[60:63]
	v_mfma_f32_16x16x32_bf16 v[56:59], v[136:139], v[200:203], v[56:59]
	v_mfma_f32_16x16x32_bf16 v[52:55], v[160:163], v[200:203], v[52:55]
	v_mfma_f32_16x16x32_bf16 v[48:51], v[136:139], v[208:211], v[48:51]
	v_mfma_f32_16x16x32_bf16 v[44:47], v[160:163], v[208:211], v[44:47]
	v_mfma_f32_16x16x32_bf16 v[40:43], v[136:139], v[216:219], v[40:43]
	v_mfma_f32_16x16x32_bf16 v[36:39], v[160:163], v[216:219], v[36:39]
	v_mfma_f32_16x16x32_bf16 v[32:35], v[172:175], v[188:191], 0
	v_mfma_f32_16x16x32_bf16 v[28:31], v[180:183], v[188:191], 0
	v_mfma_f32_16x16x32_bf16 v[24:27], v[172:175], v[196:199], 0
	v_mfma_f32_16x16x32_bf16 v[20:23], v[180:183], v[196:199], 0
	v_mfma_f32_16x16x32_bf16 v[16:19], v[172:175], v[204:207], 0
	v_mfma_f32_16x16x32_bf16 v[12:15], v[180:183], v[204:207], 0
	v_mfma_f32_16x16x32_bf16 v[8:11], v[172:175], v[212:215], 0
	v_mfma_f32_16x16x32_bf16 v[2:5], v[180:183], v[212:215], 0
	v_mfma_f32_16x16x32_bf16 v[32:35], v[176:179], v[192:195], v[32:35]
	v_mfma_f32_16x16x32_bf16 v[28:31], v[184:187], v[192:195], v[28:31]
	v_mfma_f32_16x16x32_bf16 v[24:27], v[176:179], v[200:203], v[24:27]
	v_mfma_f32_16x16x32_bf16 v[20:23], v[184:187], v[200:203], v[20:23]
	v_mfma_f32_16x16x32_bf16 v[16:19], v[176:179], v[208:211], v[16:19]
	v_mfma_f32_16x16x32_bf16 v[12:15], v[184:187], v[208:211], v[12:15]
	v_mfma_f32_16x16x32_bf16 v[8:11], v[176:179], v[216:219], v[8:11]
	v_mfma_f32_16x16x32_bf16 v[2:5], v[184:187], v[216:219], v[2:5]
	s_barrier
	s_branch .Lmid_k966
; #define PG8_STAGE(bufoff, gbase, voff) do { _Pragma("unroll") for (int _i = 0; _i < 2; ++_i) \
;         __builtin_amdgcn_global_load_lds((const unsigned*)((const char*)(gbase) + (voff)[_i]), (PG8_LAS unsigned*)(lds + (bufoff) + ldsw + _i * 8192), 16, 0, 0); } while (0)
; #define PG8_LDA(dst, b, h) do { _Pragma("unroll") for (int m = 0; m < 4; ++m) _Pragma("unroll") for (int k = 0; k < 2; ++k) dst[m][k] = *(const PG8_LAS bf16x8*)(lds + PG8_SA(b, h) + aoff + m * 2048 + k * 1024); } while (0)
; #define PG8_LDB(dst, b, h) do { _Pragma("unroll") for (int n = 0; n < 2; ++n) _Pragma("unroll") for (int k = 0; k < 2; ++k) dst[n][k] = *(const PG8_LAS bf16x8*)(lds + PG8_SB(b, h) + boff + n * 2048 + k * 1024); } while (0)
; #define PG8_WAIT_V(n) asm volatile("s_waitcnt vmcnt(" #n ")" ::: "memory")
; #define PG8_WAIT_L(n) asm volatile("s_waitcnt lgkmcnt(" #n ")" ::: "memory")
; #define PG8_BAR __builtin_amdgcn_s_barrier()
; template <class Epi, class Sched, bool ALIGN_EPI = false, bool SP2 = false, bool F8 = false>
; __device__ __forceinline__ void gemm_phase(PG8_LAS unsigned char* lds, const int K, const Sched& S, const Epi& E, const int wave) {
;     ...
;             const bool last = (t == nt - 2);
;             const char* a1 = cA + (size_t)(t + 1) * kstep;
;             const char* a2 = last ? nA : cA + (size_t)(t + 2) * kstep; const char* b2 = last ? nB : cB + (size_t)(t + 2) * kstep;
;             const char* a3 = a2 + kstep; const char* b3 = b2 + kstep;
;             asm volatile("" : "+s"(a1), "+s"(a2), "+s"(b2), "+s"(a3), "+s"(b3));
;             if (last && has_next) S.a_ready(nxt);
;             if constexpr (Epi::KHOOK) { if (cur.prob == 2 ? (t == 16) : (t == 32 || t == 48)) { if (wr == 0) PG8_BAR;
;                 E.khook(acc, cur, (cur.prob == 2 || t == 48) ? 1 : 0, wr, wc, fr, fq); if (wr == 1) PG8_BAR; } }
;             if constexpr (SP2) {
;             PG8_LDB(B0, 0, 0); PG8_LDB(B1, 0, 1); PG8_SCHED; PG8_LDA(At, 0, 0); PG8_STAGE(PG8_SA(1, 1), a1 + hstep, voffA);
;             PG8_WAIT_V(8); PG8_WAIT_L(0); PG8_BAR; PG8_MMA(0, 0, At, B0); PG8_MMA(0, 1, At, B1); PG8_BAR; PG8_SCHED;
;             PG8_LDA(At, 0, 1); PG8_STAGE(PG8_SB(0, 0), b2, voffB); PG8_STAGE(PG8_SB(0, 1), b2 + hstep, voffB); PG8_STAGE(PG8_SA(0, 0), a2, voffA);
;             PG8_WAIT_V(8); PG8_WAIT_L(0); PG8_BAR; PG8_MMA(1, 0, At, B0); PG8_MMA(1, 1, At, B1); PG8_BAR; PG8_SCHED;
.LBB0_966:
	s_add_i32 s90, s8, 2
	s_cmp_eq_u32 s85, s8
	s_cselect_b32 s42, s31, s86
	s_cselect_b32 s43, s25, s87
	s_cselect_b32 s57, s83, s89
	s_cselect_b32 s56, s84, s88
	s_add_u32 s8, s42, 0x80
	s_addc_u32 s9, s43, 0
	s_add_u32 s40, s56, 0x80
	s_addc_u32 s41, s57, 0
	s_mov_b64 s[92:93], s[6:7]
	ds_read_b128 v[132:135], v220
	ds_read_b128 v[136:139], v220 offset:1024
	ds_read_b128 v[156:159], v220 offset:2048
	ds_read_b128 v[160:163], v220 offset:3072
	ds_read_b128 v[172:175], v221
	ds_read_b128 v[176:179], v221 offset:1024
	ds_read_b128 v[180:183], v221 offset:2048
	ds_read_b128 v[184:187], v221 offset:3072
	s_add_u32 s92, s92, 0x100000
	s_addc_u32 s93, s93, 0
	s_add_i32 m0, s64, 0xc000
	ds_read_b128 v[188:191], v170
	ds_read_b128 v[192:195], v170 offset:1024
	ds_read_b128 v[196:199], v170 offset:2048
	ds_read_b128 v[200:203], v170 offset:3072
	ds_read_b128 v[204:207], v170 offset:4096
	ds_read_b128 v[208:211], v170 offset:5120
	ds_read_b128 v[212:215], v170 offset:6144
	ds_read_b128 v[216:219], v170 offset:7168
	global_load_lds_dwordx4 v140, s[92:93]
	s_add_i32 m0, s64, 0xe000
	s_nop 0
	global_load_lds_dwordx4 v144, s[92:93]
	s_waitcnt vmcnt(8)
	s_waitcnt lgkmcnt(0)
	s_setprio 1
	s_barrier
	v_mfma_f32_16x16x32_bf16 v[128:131], v[132:135], v[188:191], v[128:131]
	v_mfma_f32_16x16x32_bf16 v[124:127], v[156:159], v[188:191], v[124:127]
	v_mfma_f32_16x16x32_bf16 v[120:123], v[132:135], v[196:199], v[120:123]
	v_mfma_f32_16x16x32_bf16 v[116:119], v[156:159], v[196:199], v[116:119]
	v_mfma_f32_16x16x32_bf16 v[112:115], v[132:135], v[204:207], v[112:115]
	v_mfma_f32_16x16x32_bf16 v[108:111], v[156:159], v[204:207], v[108:111]
	v_mfma_f32_16x16x32_bf16 v[104:107], v[132:135], v[212:215], v[104:107]
	v_mfma_f32_16x16x32_bf16 v[100:103], v[156:159], v[212:215], v[100:103]
	v_mfma_f32_16x16x32_bf16 v[128:131], v[136:139], v[192:195], v[128:131]
	v_mfma_f32_16x16x32_bf16 v[124:127], v[160:163], v[192:195], v[124:127]
	v_mfma_f32_16x16x32_bf16 v[120:123], v[136:139], v[200:203], v[120:123]
	v_mfma_f32_16x16x32_bf16 v[116:119], v[160:163], v[200:203], v[116:119]
	v_mfma_f32_16x16x32_bf16 v[112:115], v[136:139], v[208:211], v[112:115]
	v_mfma_f32_16x16x32_bf16 v[108:111], v[160:163], v[208:211], v[108:111]
	v_mfma_f32_16x16x32_bf16 v[104:107], v[136:139], v[216:219], v[104:107]
	v_mfma_f32_16x16x32_bf16 v[100:103], v[160:163], v[216:219], v[100:103]
	v_mfma_f32_16x16x32_bf16 v[96:99], v[172:175], v[188:191], v[96:99]
	v_mfma_f32_16x16x32_bf16 v[92:95], v[180:183], v[188:191], v[92:95]
	v_mfma_f32_16x16x32_bf16 v[88:91], v[172:175], v[196:199], v[88:91]
	v_mfma_f32_16x16x32_bf16 v[84:87], v[180:183], v[196:199], v[84:87]
	v_mfma_f32_16x16x32_bf16 v[80:83], v[172:175], v[204:207], v[80:83]
	v_mfma_f32_16x16x32_bf16 v[76:79], v[180:183], v[204:207], v[76:79]
	v_mfma_f32_16x16x32_bf16 v[72:75], v[172:175], v[212:215], v[72:75]
	v_mfma_f32_16x16x32_bf16 v[68:71], v[180:183], v[212:215], v[68:71]
	v_mfma_f32_16x16x32_bf16 v[96:99], v[176:179], v[192:195], v[96:99]
	v_mfma_f32_16x16x32_bf16 v[92:95], v[184:187], v[192:195], v[92:95]
	v_mfma_f32_16x16x32_bf16 v[88:91], v[176:179], v[200:203], v[88:91]
	v_mfma_f32_16x16x32_bf16 v[84:87], v[184:187], v[200:203], v[84:87]
	v_mfma_f32_16x16x32_bf16 v[80:83], v[176:179], v[208:211], v[80:83]
	v_mfma_f32_16x16x32_bf16 v[76:79], v[184:187], v[208:211], v[76:79]
	v_mfma_f32_16x16x32_bf16 v[72:75], v[176:179], v[216:219], v[72:75]
	v_mfma_f32_16x16x32_bf16 v[68:71], v[184:187], v[216:219], v[68:71]
	s_barrier
	s_setprio 0
	s_add_i32 s91, s77, s63
	s_mov_b32 m0, s91
	ds_read_b128 v[188:191], v170 offset:16384
	ds_read_b128 v[192:195], v170 offset:17408
	ds_read_b128 v[196:199], v170 offset:18432
	ds_read_b128 v[200:203], v170 offset:19456
	ds_read_b128 v[204:207], v170 offset:20480
	ds_read_b128 v[208:211], v170 offset:21504
	ds_read_b128 v[212:215], v170 offset:22528
	ds_read_b128 v[216:219], v170 offset:23552
	global_load_lds_dwordx4 v142, s[56:57]
	s_add_i32 m0, s91, 0x2000
	s_nop 0
	global_load_lds_dwordx4 v146, s[56:57]
	s_add_u32 s56, s56, 0x100000
	s_addc_u32 s57, s57, 0
	s_add_i32 s91, s78, s63
	s_mov_b32 m0, s91
	s_nop 0
	global_load_lds_dwordx4 v142, s[56:57]
	s_add_i32 m0, s91, 0x2000
	s_nop 0
	global_load_lds_dwordx4 v146, s[56:57]
	s_mov_b32 m0, s64
	s_nop 0
	global_load_lds_dwordx4 v140, s[42:43]
	s_mov_b32 m0, s65
	s_nop 0
	global_load_lds_dwordx4 v144, s[42:43]
	s_waitcnt vmcnt(8)
	s_waitcnt lgkmcnt(0)
	s_setprio 1
	s_barrier
	v_mfma_f32_16x16x32_bf16 v[64:67], v[132:135], v[188:191], v[64:67]
	v_mfma_f32_16x16x32_bf16 v[60:63], v[156:159], v[188:191], v[60:63]
	v_mfma_f32_16x16x32_bf16 v[56:59], v[132:135], v[196:199], v[56:59]
	v_mfma_f32_16x16x32_bf16 v[52:55], v[156:159], v[196:199], v[52:55]
	v_mfma_f32_16x16x32_bf16 v[48:51], v[132:135], v[204:207], v[48:51]
	v_mfma_f32_16x16x32_bf16 v[44:47], v[156:159], v[204:207], v[44:47]
	v_mfma_f32_16x16x32_bf16 v[40:43], v[132:135], v[212:215], v[40:43]
	v_mfma_f32_16x16x32_bf16 v[36:39], v[156:159], v[212:215], v[36:39]
	v_mfma_f32_16x16x32_bf16 v[64:67], v[136:139], v[192:195], v[64:67]
	v_mfma_f32_16x16x32_bf16 v[60:63], v[160:163], v[192:195], v[60:63]
	v_mfma_f32_16x16x32_bf16 v[56:59], v[136:139], v[200:203], v[56:59]
	v_mfma_f32_16x16x32_bf16 v[52:55], v[160:163], v[200:203], v[52:55]
	v_mfma_f32_16x16x32_bf16 v[48:51], v[136:139], v[208:211], v[48:51]
	v_mfma_f32_16x16x32_bf16 v[44:47], v[160:163], v[208:211], v[44:47]
	v_mfma_f32_16x16x32_bf16 v[40:43], v[136:139], v[216:219], v[40:43]
	v_mfma_f32_16x16x32_bf16 v[36:39], v[160:163], v[216:219], v[36:39]
	v_mfma_f32_16x16x32_bf16 v[32:35], v[172:175], v[188:191], v[32:35]
	v_mfma_f32_16x16x32_bf16 v[28:31], v[180:183], v[188:191], v[28:31]
	v_mfma_f32_16x16x32_bf16 v[24:27], v[172:175], v[196:199], v[24:27]
	v_mfma_f32_16x16x32_bf16 v[20:23], v[180:183], v[196:199], v[20:23]
	v_mfma_f32_16x16x32_bf16 v[16:19], v[172:175], v[204:207], v[16:19]
	v_mfma_f32_16x16x32_bf16 v[12:15], v[180:183], v[204:207], v[12:15]
	v_mfma_f32_16x16x32_bf16 v[8:11], v[172:175], v[212:215], v[8:11]
	v_mfma_f32_16x16x32_bf16 v[2:5], v[180:183], v[212:215], v[4:7]
	v_mfma_f32_16x16x32_bf16 v[32:35], v[176:179], v[192:195], v[32:35]
	v_mfma_f32_16x16x32_bf16 v[28:31], v[184:187], v[192:195], v[28:31]
	v_mfma_f32_16x16x32_bf16 v[24:27], v[176:179], v[200:203], v[24:27]
	v_mfma_f32_16x16x32_bf16 v[20:23], v[184:187], v[200:203], v[20:23]
	v_mfma_f32_16x16x32_bf16 v[16:19], v[176:179], v[208:211], v[16:19]
	v_mfma_f32_16x16x32_bf16 v[12:15], v[184:187], v[208:211], v[12:15]
	v_mfma_f32_16x16x32_bf16 v[8:11], v[176:179], v[216:219], v[8:11]
	v_mfma_f32_16x16x32_bf16 v[2:5], v[184:187], v[216:219], v[2:5]
	s_barrier
; #define PG8_STAGE(bufoff, gbase, voff) do { _Pragma("unroll") for (int _i = 0; _i < 2; ++_i) \
;         __builtin_amdgcn_global_load_lds((const unsigned*)((const char*)(gbase) + (voff)[_i]), (PG8_LAS unsigned*)(lds + (bufoff) + ldsw + _i * 8192), 16, 0, 0); } while (0)
; #define PG8_LDA(dst, b, h) do { _Pragma("unroll") for (int m = 0; m < 4; ++m) _Pragma("unroll") for (int k = 0; k < 2; ++k) dst[m][k] = *(const PG8_LAS bf16x8*)(lds + PG8_SA(b, h) + aoff + m * 2048 + k * 1024); } while (0)
; #define PG8_LDB(dst, b, h) do { _Pragma("unroll") for (int n = 0; n < 2; ++n) _Pragma("unroll") for (int k = 0; k < 2; ++k) dst[n][k] = *(const PG8_LAS bf16x8*)(lds + PG8_SB(b, h) + boff + n * 2048 + k * 1024); } while (0)
; #define PG8_WAIT_V(n) asm volatile("s_waitcnt vmcnt(" #n ")" ::: "memory")
; #define PG8_WAIT_L(n) asm volatile("s_waitcnt lgkmcnt(" #n ")" ::: "memory")
; #define PG8_BAR __builtin_amdgcn_s_barrier()
; #define PG8_SCHED __builtin_amdgcn_sched_barrier(0)
; template <class Epi, class Sched, bool ALIGN_EPI = false, bool SP2 = false, bool F8 = false>
; __device__ __forceinline__ void gemm_phase(PG8_LAS unsigned char* lds, const int K, const Sched& S, const Epi& E, const int wave) {
;     ...
;             PG8_LDB(B0, 1, 0); PG8_LDB(B1, 1, 1); PG8_SCHED; PG8_LDA(At, 1, 0); PG8_STAGE(PG8_SA(0, 1), a2 + hstep, voffA);
;             PG8_WAIT_V(8); PG8_WAIT_L(0); PG8_BAR; PG8_MMA(0, 0, At, B0); PG8_MMA(0, 1, At, B1); PG8_BAR; PG8_SCHED;
;             PG8_LDA(At, 1, 1); PG8_STAGE(PG8_SB(1, 0), b3, voffB); PG8_STAGE(PG8_SB(1, 1), b3 + hstep, voffB); PG8_STAGE(PG8_SA(1, 0), a3, voffA);
;             PG8_WAIT_V(8); PG8_WAIT_L(0); PG8_BAR; PG8_MMA(1, 0, At, B0); PG8_MMA(1, 1, At, B1); PG8_BAR; PG8_SCHED;
.Lmid_k966:
	s_setprio 0
	s_add_i32 s56, 0, 0x18000
	s_add_i32 s57, 0, 0x1c000
	ds_read_b128 v[132:135], v222
	ds_read_b128 v[136:139], v222 offset:1024
	ds_read_b128 v[156:159], v222 offset:2048
	ds_read_b128 v[160:163], v222 offset:3072
	ds_read_b128 v[172:175], v223
	ds_read_b128 v[176:179], v223 offset:1024
	ds_read_b128 v[180:183], v223 offset:2048
	ds_read_b128 v[184:187], v223 offset:3072
	s_add_u32 s42, s42, 0x100000
	s_addc_u32 s43, s43, 0
	s_mov_b32 m0, s66
	ds_read_b128 v[188:191], v170 offset:32768
	ds_read_b128 v[192:195], v170 offset:33792
	ds_read_b128 v[196:199], v170 offset:34816
	ds_read_b128 v[200:203], v170 offset:35840
	ds_read_b128 v[204:207], v170 offset:36864
	ds_read_b128 v[208:211], v170 offset:37888
	ds_read_b128 v[212:215], v170 offset:38912
	ds_read_b128 v[216:219], v170 offset:39936
	global_load_lds_dwordx4 v140, s[42:43]
	s_mov_b32 m0, s67
	s_nop 0
	global_load_lds_dwordx4 v144, s[42:43]
	s_waitcnt vmcnt(8)
	s_waitcnt lgkmcnt(0)
	s_setprio 1
	s_barrier
	v_mfma_f32_16x16x32_bf16 v[128:131], v[132:135], v[188:191], v[128:131]
	v_mfma_f32_16x16x32_bf16 v[124:127], v[156:159], v[188:191], v[124:127]
	v_mfma_f32_16x16x32_bf16 v[120:123], v[132:135], v[196:199], v[120:123]
	v_mfma_f32_16x16x32_bf16 v[116:119], v[156:159], v[196:199], v[116:119]
	v_mfma_f32_16x16x32_bf16 v[112:115], v[132:135], v[204:207], v[112:115]
	v_mfma_f32_16x16x32_bf16 v[108:111], v[156:159], v[204:207], v[108:111]
	v_mfma_f32_16x16x32_bf16 v[104:107], v[132:135], v[212:215], v[104:107]
	v_mfma_f32_16x16x32_bf16 v[100:103], v[156:159], v[212:215], v[100:103]
	v_mfma_f32_16x16x32_bf16 v[128:131], v[136:139], v[192:195], v[128:131]
	v_mfma_f32_16x16x32_bf16 v[124:127], v[160:163], v[192:195], v[124:127]
	v_mfma_f32_16x16x32_bf16 v[120:123], v[136:139], v[200:203], v[120:123]
	v_mfma_f32_16x16x32_bf16 v[116:119], v[160:163], v[200:203], v[116:119]
	v_mfma_f32_16x16x32_bf16 v[112:115], v[136:139], v[208:211], v[112:115]
	v_mfma_f32_16x16x32_bf16 v[108:111], v[160:163], v[208:211], v[108:111]
	v_mfma_f32_16x16x32_bf16 v[104:107], v[136:139], v[216:219], v[104:107]
	v_mfma_f32_16x16x32_bf16 v[100:103], v[160:163], v[216:219], v[100:103]
	v_mfma_f32_16x16x32_bf16 v[96:99], v[172:175], v[188:191], v[96:99]
	v_mfma_f32_16x16x32_bf16 v[92:95], v[180:183], v[188:191], v[92:95]
	v_mfma_f32_16x16x32_bf16 v[88:91], v[172:175], v[196:199], v[88:91]
	v_mfma_f32_16x16x32_bf16 v[84:87], v[180:183], v[196:199], v[84:87]
	v_mfma_f32_16x16x32_bf16 v[80:83], v[172:175], v[204:207], v[80:83]
	v_mfma_f32_16x16x32_bf16 v[76:79], v[180:183], v[204:207], v[76:79]
	v_mfma_f32_16x16x32_bf16 v[72:75], v[172:175], v[212:215], v[72:75]
	v_mfma_f32_16x16x32_bf16 v[68:71], v[180:183], v[212:215], v[68:71]
	v_mfma_f32_16x16x32_bf16 v[96:99], v[176:179], v[192:195], v[96:99]
	v_mfma_f32_16x16x32_bf16 v[92:95], v[184:187], v[192:195], v[92:95]
	v_mfma_f32_16x16x32_bf16 v[88:91], v[176:179], v[200:203], v[88:91]
	v_mfma_f32_16x16x32_bf16 v[84:87], v[184:187], v[200:203], v[84:87]
	v_mfma_f32_16x16x32_bf16 v[80:83], v[176:179], v[208:211], v[80:83]
	v_mfma_f32_16x16x32_bf16 v[76:79], v[184:187], v[208:211], v[76:79]
	v_mfma_f32_16x16x32_bf16 v[72:75], v[176:179], v[216:219], v[72:75]
	v_mfma_f32_16x16x32_bf16 v[68:71], v[184:187], v[216:219], v[68:71]
	s_barrier
	s_setprio 0
	s_add_i32 s42, s56, s63
	s_mov_b32 m0, s42
	ds_read_b128 v[188:191], v170 offset:49152
	ds_read_b128 v[192:195], v170 offset:50176
	ds_read_b128 v[196:199], v170 offset:51200
	ds_read_b128 v[200:203], v170 offset:52224
	ds_read_b128 v[204:207], v170 offset:53248
	ds_read_b128 v[208:211], v170 offset:54272
	ds_read_b128 v[212:215], v170 offset:55296
	ds_read_b128 v[216:219], v170 offset:56320
	global_load_lds_dwordx4 v142, s[40:41]
	s_add_i32 m0, s42, 0x2000
	s_nop 0
	global_load_lds_dwordx4 v146, s[40:41]
	s_add_u32 s40, s40, 0x100000
	s_addc_u32 s41, s41, 0
	s_add_i32 s42, s57, s63
	s_mov_b32 m0, s42
	s_nop 0
	global_load_lds_dwordx4 v142, s[40:41]
	s_add_i32 m0, s42, 0x2000
	s_nop 0
	global_load_lds_dwordx4 v146, s[40:41]
	s_mov_b32 m0, s74
	s_nop 0
	global_load_lds_dwordx4 v140, s[8:9]
	s_mov_b32 m0, s76
	s_nop 0
	global_load_lds_dwordx4 v144, s[8:9]
	s_waitcnt vmcnt(8)
	s_waitcnt lgkmcnt(0)
	s_setprio 1
	s_barrier
	v_mfma_f32_16x16x32_bf16 v[64:67], v[132:135], v[188:191], v[64:67]
	v_mfma_f32_16x16x32_bf16 v[60:63], v[156:159], v[188:191], v[60:63]
	v_mfma_f32_16x16x32_bf16 v[56:59], v[132:135], v[196:199], v[56:59]
	v_mfma_f32_16x16x32_bf16 v[52:55], v[156:159], v[196:199], v[52:55]
	v_mfma_f32_16x16x32_bf16 v[48:51], v[132:135], v[204:207], v[48:51]
	v_mfma_f32_16x16x32_bf16 v[44:47], v[156:159], v[204:207], v[44:47]
	v_mfma_f32_16x16x32_bf16 v[40:43], v[132:135], v[212:215], v[40:43]
	v_mfma_f32_16x16x32_bf16 v[36:39], v[156:159], v[212:215], v[36:39]
	v_mfma_f32_16x16x32_bf16 v[64:67], v[136:139], v[192:195], v[64:67]
	v_mfma_f32_16x16x32_bf16 v[60:63], v[160:163], v[192:195], v[60:63]
	v_mfma_f32_16x16x32_bf16 v[56:59], v[136:139], v[200:203], v[56:59]
	v_mfma_f32_16x16x32_bf16 v[52:55], v[160:163], v[200:203], v[52:55]
	v_mfma_f32_16x16x32_bf16 v[48:51], v[136:139], v[208:211], v[48:51]
	v_mfma_f32_16x16x32_bf16 v[44:47], v[160:163], v[208:211], v[44:47]
	v_mfma_f32_16x16x32_bf16 v[40:43], v[136:139], v[216:219], v[40:43]
	v_mfma_f32_16x16x32_bf16 v[36:39], v[160:163], v[216:219], v[36:39]
	v_mfma_f32_16x16x32_bf16 v[32:35], v[172:175], v[188:191], v[32:35]
	v_mfma_f32_16x16x32_bf16 v[28:31], v[180:183], v[188:191], v[28:31]
	v_mfma_f32_16x16x32_bf16 v[24:27], v[172:175], v[196:199], v[24:27]
	v_mfma_f32_16x16x32_bf16 v[20:23], v[180:183], v[196:199], v[20:23]
	v_mfma_f32_16x16x32_bf16 v[16:19], v[172:175], v[204:207], v[16:19]
	v_mfma_f32_16x16x32_bf16 v[12:15], v[180:183], v[204:207], v[12:15]
	v_mfma_f32_16x16x32_bf16 v[6:9], v[172:175], v[212:215], v[8:11]
	v_mfma_f32_16x16x32_bf16 v[2:5], v[180:183], v[212:215], v[2:5]
	v_mfma_f32_16x16x32_bf16 v[32:35], v[176:179], v[192:195], v[32:35]
	v_mfma_f32_16x16x32_bf16 v[28:31], v[184:187], v[192:195], v[28:31]
	v_mfma_f32_16x16x32_bf16 v[24:27], v[176:179], v[200:203], v[24:27]
	v_mfma_f32_16x16x32_bf16 v[20:23], v[184:187], v[200:203], v[20:23]
	v_mfma_f32_16x16x32_bf16 v[16:19], v[176:179], v[208:211], v[16:19]
	v_mfma_f32_16x16x32_bf16 v[12:15], v[184:187], v[208:211], v[12:15]
	v_mfma_f32_16x16x32_bf16 v[8:11], v[176:179], v[216:219], v[6:9]
	v_mfma_f32_16x16x32_bf16 v[4:7], v[184:187], v[216:219], v[2:5]
	s_barrier
	s_setprio 0
	s_add_u32 s86, s86, 0x100
	s_addc_u32 s87, s87, 0
	s_add_u32 s88, s88, 0x100
	s_addc_u32 s89, s89, 0
	s_add_u32 s6, s6, 0x100
	s_addc_u32 s7, s7, 0
	s_cmp_ge_i32 s90, s62
	s_mov_b32 s8, s90
	s_cbranch_scc0 .LBB0_966

; #define PG8_STAGE(bufoff, gbase, voff) do { _Pragma("unroll") for (int _i = 0; _i < 2; ++_i) \
;         __builtin_amdgcn_global_load_lds((const unsigned*)((const char*)(gbase) + (voff)[_i]), (PG8_LAS unsigned*)(lds + (bufoff) + ldsw + _i * 8192), 16, 0, 0); } while (0)
; #define PG8_LDA(dst, b, h) do { _Pragma("unroll") for (int m = 0; m < 4; ++m) _Pragma("unroll") for (int k = 0; k < 2; ++k) dst[m][k] = *(const PG8_LAS bf16x8*)(lds + PG8_SA(b, h) + aoff + m * 2048 + k * 1024); } while (0)
; #define PG8_LDB(dst, b, h) do { _Pragma("unroll") for (int n = 0; n < 2; ++n) _Pragma("unroll") for (int k = 0; k < 2; ++k) dst[n][k] = *(const PG8_LAS bf16x8*)(lds + PG8_SB(b, h) + boff + n * 2048 + k * 1024); } while (0)
; #define PG8_WAIT_V(n) asm volatile("s_waitcnt vmcnt(" #n ")" ::: "memory")
; #define PG8_WAIT_L(n) asm volatile("s_waitcnt lgkmcnt(" #n ")" ::: "memory")
; #define PG8_BAR __builtin_amdgcn_s_barrier()
; template <class Epi, class Sched, bool ALIGN_EPI = false, bool SP2 = false, bool F8 = false>
; __device__ __forceinline__ void gemm_phase(PG8_LAS unsigned char* lds, const int K, const Sched& S, const Epi& E, const int wave) {
;     ...
;             const bool last = (t == nt - 2);
;             const char* a1 = cA + (size_t)(t + 1) * kstep;
;             const char* a2 = last ? nA : cA + (size_t)(t + 2) * kstep; const char* b2 = last ? nB : cB + (size_t)(t + 2) * kstep;
;             const char* a3 = a2 + kstep; const char* b3 = b2 + kstep;
;             asm volatile("" : "+s"(a1), "+s"(a2), "+s"(b2), "+s"(a3), "+s"(b3));
;             if (last && has_next) S.a_ready(nxt);
;             if constexpr (Epi::KHOOK) { if (cur.prob == 2 ? (t == 16) : (t == 32 || t == 48)) { if (wr == 0) PG8_BAR;
;                 E.khook(acc, cur, (cur.prob == 2 || t == 48) ? 1 : 0, wr, wc, fr, fq); if (wr == 1) PG8_BAR; } }
;             if constexpr (SP2) {
;             PG8_LDB(B0, 0, 0); PG8_LDB(B1, 0, 1); PG8_SCHED; PG8_LDA(At, 0, 0); PG8_STAGE(PG8_SA(1, 1), a1 + hstep, voffA);
;             PG8_WAIT_V(8); PG8_WAIT_L(0); PG8_BAR; PG8_MMA(0, 0, At, B0); PG8_MMA(0, 1, At, B1); PG8_BAR; PG8_SCHED;
;             PG8_LDA(At, 0, 1); PG8_STAGE(PG8_SB(0, 0), b2, voffB); PG8_STAGE(PG8_SB(0, 1), b2 + hstep, voffB); PG8_STAGE(PG8_SA(0, 0), a2, voffA);
;             PG8_WAIT_V(8); PG8_WAIT_L(0); PG8_BAR; PG8_MMA(1, 0, At, B0); PG8_MMA(1, 1, At, B1); PG8_BAR; PG8_SCHED;
.Lpeel_k1240:
	v_add_u32_e32 v210, s59, v146
	v_add_u32_e32 v211, s60, v146
	v_add_u32_e32 v212, 0x18000, v146
	v_add_u32_e32 v213, 0x1c000, v146
	s_add_u32 s25, s10, s38
	s_addc_u32 s40, s11, s39
	s_add_u32 s64, s25, 0xffffff80
	s_addc_u32 s65, s40, -1
	s_add_u32 s41, s12, s38
	s_addc_u32 s42, s13, s39
	s_cmp_eq_u32 s23, 60
	s_cselect_b32 s44, s30, s25
	s_cselect_b32 s45, s31, s40
	s_cselect_b32 s53, s37, s42
	s_cselect_b32 s52, s36, s41
	s_add_u32 s40, s44, 0x80
	s_addc_u32 s41, s45, 0
	s_add_u32 s42, s52, 0x80
	s_addc_u32 s43, s53, 0
	ds_read_b128 v[140:143], v210
	ds_read_b128 v[150:153], v210 offset:1024
	ds_read_b128 v[154:157], v210 offset:2048
	ds_read_b128 v[158:161], v210 offset:3072
	ds_read_b128 v[162:165], v211
	ds_read_b128 v[166:169], v211 offset:1024
	ds_read_b128 v[170:173], v211 offset:2048
	ds_read_b128 v[174:177], v211 offset:3072
	s_add_u32 s64, s64, 0x100000
	s_addc_u32 s65, s65, 0
	s_add_i32 m0, s9, 0xc000
	ds_read_b128 v[178:181], v148
	ds_read_b128 v[182:185], v148 offset:1024
	ds_read_b128 v[186:189], v148 offset:2048
	ds_read_b128 v[190:193], v148 offset:3072
	ds_read_b128 v[194:197], v148 offset:4096
	ds_read_b128 v[198:201], v148 offset:5120
	ds_read_b128 v[202:205], v148 offset:6144
	ds_read_b128 v[206:209], v148 offset:7168
	global_load_lds_dwordx4 v134, s[64:65]
	s_add_i32 m0, s9, 0xe000
	s_nop 0
	global_load_lds_dwordx4 v130, s[64:65]
	s_waitcnt vmcnt(8)
	s_waitcnt lgkmcnt(0)
	s_setprio 1
	s_barrier
	v_mfma_f32_16x16x32_bf16 v[124:127], v[140:143], v[178:181], 0
	v_mfma_f32_16x16x32_bf16 v[120:123], v[154:157], v[178:181], 0
	v_mfma_f32_16x16x32_bf16 v[116:119], v[140:143], v[186:189], 0
	v_mfma_f32_16x16x32_bf16 v[112:115], v[154:157], v[186:189], 0
	v_mfma_f32_16x16x32_bf16 v[108:111], v[140:143], v[194:197], 0
	v_mfma_f32_16x16x32_bf16 v[104:107], v[154:157], v[194:197], 0
	v_mfma_f32_16x16x32_bf16 v[100:103], v[140:143], v[202:205], 0
	v_mfma_f32_16x16x32_bf16 v[96:99], v[154:157], v[202:205], 0
	v_mfma_f32_16x16x32_bf16 v[124:127], v[150:153], v[182:185], v[124:127]
	v_mfma_f32_16x16x32_bf16 v[120:123], v[158:161], v[182:185], v[120:123]
	v_mfma_f32_16x16x32_bf16 v[116:119], v[150:153], v[190:193], v[116:119]
	v_mfma_f32_16x16x32_bf16 v[112:115], v[158:161], v[190:193], v[112:115]
	v_mfma_f32_16x16x32_bf16 v[108:111], v[150:153], v[198:201], v[108:111]
	v_mfma_f32_16x16x32_bf16 v[104:107], v[158:161], v[198:201], v[104:107]
	v_mfma_f32_16x16x32_bf16 v[100:103], v[150:153], v[206:209], v[100:103]
	v_mfma_f32_16x16x32_bf16 v[96:99], v[158:161], v[206:209], v[96:99]
	v_mfma_f32_16x16x32_bf16 v[92:95], v[162:165], v[178:181], 0
	v_mfma_f32_16x16x32_bf16 v[88:91], v[170:173], v[178:181], 0
	v_mfma_f32_16x16x32_bf16 v[84:87], v[162:165], v[186:189], 0
	v_mfma_f32_16x16x32_bf16 v[80:83], v[170:173], v[186:189], 0
	v_mfma_f32_16x16x32_bf16 v[76:79], v[162:165], v[194:197], 0
	v_mfma_f32_16x16x32_bf16 v[72:75], v[170:173], v[194:197], 0
	v_mfma_f32_16x16x32_bf16 v[68:71], v[162:165], v[202:205], 0
	v_mfma_f32_16x16x32_bf16 v[64:67], v[170:173], v[202:205], 0
	v_mfma_f32_16x16x32_bf16 v[92:95], v[166:169], v[182:185], v[92:95]
	v_mfma_f32_16x16x32_bf16 v[88:91], v[174:177], v[182:185], v[88:91]
	v_mfma_f32_16x16x32_bf16 v[84:87], v[166:169], v[190:193], v[84:87]
	v_mfma_f32_16x16x32_bf16 v[80:83], v[174:177], v[190:193], v[80:83]
	v_mfma_f32_16x16x32_bf16 v[76:79], v[166:169], v[198:201], v[76:79]
	v_mfma_f32_16x16x32_bf16 v[72:75], v[174:177], v[198:201], v[72:75]
	v_mfma_f32_16x16x32_bf16 v[68:71], v[166:169], v[206:209], v[68:71]
	v_mfma_f32_16x16x32_bf16 v[64:67], v[174:177], v[206:209], v[64:67]
	s_barrier
	s_setprio 0
	s_add_i32 s25, s59, s48
	s_mov_b32 m0, s25
	ds_read_b128 v[178:181], v148 offset:16384
	ds_read_b128 v[182:185], v148 offset:17408
	ds_read_b128 v[186:189], v148 offset:18432
	ds_read_b128 v[190:193], v148 offset:19456
	ds_read_b128 v[194:197], v148 offset:20480
	ds_read_b128 v[198:201], v148 offset:21504
	ds_read_b128 v[202:205], v148 offset:22528
	ds_read_b128 v[206:209], v148 offset:23552
	global_load_lds_dwordx4 v132, s[52:53]
	s_add_i32 m0, s25, 0x2000
	s_nop 0
	global_load_lds_dwordx4 v128, s[52:53]
	s_add_u32 s52, s52, 0x100000
	s_addc_u32 s53, s53, 0
	s_add_i32 s25, s60, s48
	s_mov_b32 m0, s25
	s_nop 0
	global_load_lds_dwordx4 v132, s[52:53]
	s_add_i32 m0, s25, 0x2000
	s_nop 0
	global_load_lds_dwordx4 v128, s[52:53]
	s_mov_b32 m0, s9
	s_nop 0
	global_load_lds_dwordx4 v134, s[44:45]
	s_mov_b32 m0, s50
	s_nop 0
	global_load_lds_dwordx4 v130, s[44:45]
	s_waitcnt vmcnt(8)
	s_waitcnt lgkmcnt(0)
	s_setprio 1
	s_barrier
	v_mfma_f32_16x16x32_bf16 v[60:63], v[140:143], v[178:181], 0
	v_mfma_f32_16x16x32_bf16 v[56:59], v[154:157], v[178:181], 0
	v_mfma_f32_16x16x32_bf16 v[52:55], v[140:143], v[186:189], 0
	v_mfma_f32_16x16x32_bf16 v[48:51], v[154:157], v[186:189], 0
	v_mfma_f32_16x16x32_bf16 v[44:47], v[140:143], v[194:197], 0
	v_mfma_f32_16x16x32_bf16 v[40:43], v[154:157], v[194:197], 0
	v_mfma_f32_16x16x32_bf16 v[36:39], v[140:143], v[202:205], 0
	v_mfma_f32_16x16x32_bf16 v[32:35], v[154:157], v[202:205], 0
	v_mfma_f32_16x16x32_bf16 v[60:63], v[150:153], v[182:185], v[60:63]
	v_mfma_f32_16x16x32_bf16 v[56:59], v[158:161], v[182:185], v[56:59]
	v_mfma_f32_16x16x32_bf16 v[52:55], v[150:153], v[190:193], v[52:55]
	v_mfma_f32_16x16x32_bf16 v[48:51], v[158:161], v[190:193], v[48:51]
	v_mfma_f32_16x16x32_bf16 v[44:47], v[150:153], v[198:201], v[44:47]
	v_mfma_f32_16x16x32_bf16 v[40:43], v[158:161], v[198:201], v[40:43]
	v_mfma_f32_16x16x32_bf16 v[36:39], v[150:153], v[206:209], v[36:39]
	v_mfma_f32_16x16x32_bf16 v[32:35], v[158:161], v[206:209], v[32:35]
	v_mfma_f32_16x16x32_bf16 v[28:31], v[162:165], v[178:181], 0
	v_mfma_f32_16x16x32_bf16 v[24:27], v[170:173], v[178:181], 0
	v_mfma_f32_16x16x32_bf16 v[20:23], v[162:165], v[186:189], 0
	v_mfma_f32_16x16x32_bf16 v[16:19], v[170:173], v[186:189], 0
	v_mfma_f32_16x16x32_bf16 v[12:15], v[162:165], v[194:197], 0
	v_mfma_f32_16x16x32_bf16 v[8:11], v[170:173], v[194:197], 0
	v_mfma_f32_16x16x32_bf16 v[4:7], v[162:165], v[202:205], 0
	v_mfma_f32_16x16x32_bf16 v[0:3], v[170:173], v[202:205], 0
	v_mfma_f32_16x16x32_bf16 v[28:31], v[166:169], v[182:185], v[28:31]
	v_mfma_f32_16x16x32_bf16 v[24:27], v[174:177], v[182:185], v[24:27]
	v_mfma_f32_16x16x32_bf16 v[20:23], v[166:169], v[190:193], v[20:23]
	v_mfma_f32_16x16x32_bf16 v[16:19], v[174:177], v[190:193], v[16:19]
	v_mfma_f32_16x16x32_bf16 v[12:15], v[166:169], v[198:201], v[12:15]
	v_mfma_f32_16x16x32_bf16 v[8:11], v[174:177], v[198:201], v[8:11]
	v_mfma_f32_16x16x32_bf16 v[4:7], v[166:169], v[206:209], v[4:7]
	v_mfma_f32_16x16x32_bf16 v[0:3], v[174:177], v[206:209], v[0:3]
	s_barrier
	s_branch .Lmid_k1240
; #define PG8_STAGE(bufoff, gbase, voff) do { _Pragma("unroll") for (int _i = 0; _i < 2; ++_i) \
;         __builtin_amdgcn_global_load_lds((const unsigned*)((const char*)(gbase) + (voff)[_i]), (PG8_LAS unsigned*)(lds + (bufoff) + ldsw + _i * 8192), 16, 0, 0); } while (0)
; #define PG8_LDA(dst, b, h) do { _Pragma("unroll") for (int m = 0; m < 4; ++m) _Pragma("unroll") for (int k = 0; k < 2; ++k) dst[m][k] = *(const PG8_LAS bf16x8*)(lds + PG8_SA(b, h) + aoff + m * 2048 + k * 1024); } while (0)
; #define PG8_LDB(dst, b, h) do { _Pragma("unroll") for (int n = 0; n < 2; ++n) _Pragma("unroll") for (int k = 0; k < 2; ++k) dst[n][k] = *(const PG8_LAS bf16x8*)(lds + PG8_SB(b, h) + boff + n * 2048 + k * 1024); } while (0)
; #define PG8_WAIT_V(n) asm volatile("s_waitcnt vmcnt(" #n ")" ::: "memory")
; #define PG8_WAIT_L(n) asm volatile("s_waitcnt lgkmcnt(" #n ")" ::: "memory")
; #define PG8_BAR __builtin_amdgcn_s_barrier()
; template <class Epi, class Sched, bool ALIGN_EPI = false, bool SP2 = false, bool F8 = false>
; __device__ __forceinline__ void gemm_phase(PG8_LAS unsigned char* lds, const int K, const Sched& S, const Epi& E, const int wave) {
;     ...
;             const bool last = (t == nt - 2);
;             const char* a1 = cA + (size_t)(t + 1) * kstep;
;             const char* a2 = last ? nA : cA + (size_t)(t + 2) * kstep; const char* b2 = last ? nB : cB + (size_t)(t + 2) * kstep;
;             const char* a3 = a2 + kstep; const char* b3 = b2 + kstep;
;             asm volatile("" : "+s"(a1), "+s"(a2), "+s"(b2), "+s"(a3), "+s"(b3));
;             if (last && has_next) S.a_ready(nxt);
;             if constexpr (Epi::KHOOK) { if (cur.prob == 2 ? (t == 16) : (t == 32 || t == 48)) { if (wr == 0) PG8_BAR;
;                 E.khook(acc, cur, (cur.prob == 2 || t == 48) ? 1 : 0, wr, wc, fr, fq); if (wr == 1) PG8_BAR; } }
;             if constexpr (SP2) {
;             PG8_LDB(B0, 0, 0); PG8_LDB(B1, 0, 1); PG8_SCHED; PG8_LDA(At, 0, 0); PG8_STAGE(PG8_SA(1, 1), a1 + hstep, voffA);
;             PG8_WAIT_V(8); PG8_WAIT_L(0); PG8_BAR; PG8_MMA(0, 0, At, B0); PG8_MMA(0, 1, At, B1); PG8_BAR; PG8_SCHED;
;             PG8_LDA(At, 0, 1); PG8_STAGE(PG8_SB(0, 0), b2, voffB); PG8_STAGE(PG8_SB(0, 1), b2 + hstep, voffB); PG8_STAGE(PG8_SA(0, 0), a2, voffA);
;             PG8_WAIT_V(8); PG8_WAIT_L(0); PG8_BAR; PG8_MMA(1, 0, At, B0); PG8_MMA(1, 1, At, B1); PG8_BAR; PG8_SCHED;
.LBB0_1240:
	s_add_u32 s25, s10, s38
	s_addc_u32 s40, s11, s39
	s_add_u32 s64, s25, 0xffffff80
	s_addc_u32 s65, s40, -1
	s_add_u32 s41, s12, s38
	s_addc_u32 s42, s13, s39
	s_cmp_eq_u32 s23, 60
	s_cselect_b32 s44, s30, s25
	s_cselect_b32 s45, s31, s40
	s_cselect_b32 s53, s37, s42
	s_cselect_b32 s52, s36, s41
	s_add_u32 s40, s44, 0x80
	s_addc_u32 s41, s45, 0
	s_add_u32 s42, s52, 0x80
	s_addc_u32 s43, s53, 0
	ds_read_b128 v[140:143], v210
	ds_read_b128 v[150:153], v210 offset:1024
	ds_read_b128 v[154:157], v210 offset:2048
	ds_read_b128 v[158:161], v210 offset:3072
	ds_read_b128 v[162:165], v211
	ds_read_b128 v[166:169], v211 offset:1024
	ds_read_b128 v[170:173], v211 offset:2048
	ds_read_b128 v[174:177], v211 offset:3072
	s_add_u32 s64, s64, 0x100000
	s_addc_u32 s65, s65, 0
	s_add_i32 m0, s9, 0xc000
	ds_read_b128 v[178:181], v148
	ds_read_b128 v[182:185], v148 offset:1024
	ds_read_b128 v[186:189], v148 offset:2048
	ds_read_b128 v[190:193], v148 offset:3072
	ds_read_b128 v[194:197], v148 offset:4096
	ds_read_b128 v[198:201], v148 offset:5120
	ds_read_b128 v[202:205], v148 offset:6144
	ds_read_b128 v[206:209], v148 offset:7168
	global_load_lds_dwordx4 v134, s[64:65]
	s_add_i32 m0, s9, 0xe000
	s_nop 0
	global_load_lds_dwordx4 v130, s[64:65]
	s_waitcnt vmcnt(8)
	s_waitcnt lgkmcnt(0)
	s_setprio 1
	s_barrier
	v_mfma_f32_16x16x32_bf16 v[124:127], v[140:143], v[178:181], v[124:127]
	v_mfma_f32_16x16x32_bf16 v[120:123], v[154:157], v[178:181], v[120:123]
	v_mfma_f32_16x16x32_bf16 v[116:119], v[140:143], v[186:189], v[116:119]
	v_mfma_f32_16x16x32_bf16 v[112:115], v[154:157], v[186:189], v[112:115]
	v_mfma_f32_16x16x32_bf16 v[108:111], v[140:143], v[194:197], v[108:111]
	v_mfma_f32_16x16x32_bf16 v[104:107], v[154:157], v[194:197], v[104:107]
	v_mfma_f32_16x16x32_bf16 v[100:103], v[140:143], v[202:205], v[100:103]
	v_mfma_f32_16x16x32_bf16 v[96:99], v[154:157], v[202:205], v[96:99]
	v_mfma_f32_16x16x32_bf16 v[124:127], v[150:153], v[182:185], v[124:127]
	v_mfma_f32_16x16x32_bf16 v[120:123], v[158:161], v[182:185], v[120:123]
	v_mfma_f32_16x16x32_bf16 v[116:119], v[150:153], v[190:193], v[116:119]
	v_mfma_f32_16x16x32_bf16 v[112:115], v[158:161], v[190:193], v[112:115]
	v_mfma_f32_16x16x32_bf16 v[108:111], v[150:153], v[198:201], v[108:111]
	v_mfma_f32_16x16x32_bf16 v[104:107], v[158:161], v[198:201], v[104:107]
	v_mfma_f32_16x16x32_bf16 v[100:103], v[150:153], v[206:209], v[100:103]
	v_mfma_f32_16x16x32_bf16 v[96:99], v[158:161], v[206:209], v[96:99]
	v_mfma_f32_16x16x32_bf16 v[92:95], v[162:165], v[178:181], v[92:95]
	v_mfma_f32_16x16x32_bf16 v[88:91], v[170:173], v[178:181], v[88:91]
	v_mfma_f32_16x16x32_bf16 v[84:87], v[162:165], v[186:189], v[84:87]
	v_mfma_f32_16x16x32_bf16 v[80:83], v[170:173], v[186:189], v[80:83]
	v_mfma_f32_16x16x32_bf16 v[76:79], v[162:165], v[194:197], v[76:79]
	v_mfma_f32_16x16x32_bf16 v[72:75], v[170:173], v[194:197], v[72:75]
	v_mfma_f32_16x16x32_bf16 v[68:71], v[162:165], v[202:205], v[68:71]
	v_mfma_f32_16x16x32_bf16 v[64:67], v[170:173], v[202:205], v[64:67]
	v_mfma_f32_16x16x32_bf16 v[92:95], v[166:169], v[182:185], v[92:95]
	v_mfma_f32_16x16x32_bf16 v[88:91], v[174:177], v[182:185], v[88:91]
	v_mfma_f32_16x16x32_bf16 v[84:87], v[166:169], v[190:193], v[84:87]
	v_mfma_f32_16x16x32_bf16 v[80:83], v[174:177], v[190:193], v[80:83]
	v_mfma_f32_16x16x32_bf16 v[76:79], v[166:169], v[198:201], v[76:79]
	v_mfma_f32_16x16x32_bf16 v[72:75], v[174:177], v[198:201], v[72:75]
	v_mfma_f32_16x16x32_bf16 v[68:71], v[166:169], v[206:209], v[68:71]
	v_mfma_f32_16x16x32_bf16 v[64:67], v[174:177], v[206:209], v[64:67]
	s_barrier
	s_setprio 0
	s_add_i32 s25, s59, s48
	s_mov_b32 m0, s25
	ds_read_b128 v[178:181], v148 offset:16384
	ds_read_b128 v[182:185], v148 offset:17408
	ds_read_b128 v[186:189], v148 offset:18432
	ds_read_b128 v[190:193], v148 offset:19456
	ds_read_b128 v[194:197], v148 offset:20480
	ds_read_b128 v[198:201], v148 offset:21504
	ds_read_b128 v[202:205], v148 offset:22528
	ds_read_b128 v[206:209], v148 offset:23552
	global_load_lds_dwordx4 v132, s[52:53]
	s_add_i32 m0, s25, 0x2000
	s_nop 0
	global_load_lds_dwordx4 v128, s[52:53]
	s_add_u32 s52, s52, 0x100000
	s_addc_u32 s53, s53, 0
	s_add_i32 s25, s60, s48
	s_mov_b32 m0, s25
	s_nop 0
	global_load_lds_dwordx4 v132, s[52:53]
	s_add_i32 m0, s25, 0x2000
	s_nop 0
	global_load_lds_dwordx4 v128, s[52:53]
	s_mov_b32 m0, s9
	s_nop 0
	global_load_lds_dwordx4 v134, s[44:45]
	s_mov_b32 m0, s50
	s_nop 0
	global_load_lds_dwordx4 v130, s[44:45]
	s_waitcnt vmcnt(8)
	s_waitcnt lgkmcnt(0)
	s_setprio 1
	s_barrier
	v_mfma_f32_16x16x32_bf16 v[60:63], v[140:143], v[178:181], v[60:63]
	v_mfma_f32_16x16x32_bf16 v[56:59], v[154:157], v[178:181], v[56:59]
	v_mfma_f32_16x16x32_bf16 v[52:55], v[140:143], v[186:189], v[52:55]
	v_mfma_f32_16x16x32_bf16 v[48:51], v[154:157], v[186:189], v[48:51]
	v_mfma_f32_16x16x32_bf16 v[44:47], v[140:143], v[194:197], v[44:47]
	v_mfma_f32_16x16x32_bf16 v[40:43], v[154:157], v[194:197], v[40:43]
	v_mfma_f32_16x16x32_bf16 v[36:39], v[140:143], v[202:205], v[36:39]
	v_mfma_f32_16x16x32_bf16 v[32:35], v[154:157], v[202:205], v[32:35]
	v_mfma_f32_16x16x32_bf16 v[60:63], v[150:153], v[182:185], v[60:63]
	v_mfma_f32_16x16x32_bf16 v[56:59], v[158:161], v[182:185], v[56:59]
	v_mfma_f32_16x16x32_bf16 v[52:55], v[150:153], v[190:193], v[52:55]
	v_mfma_f32_16x16x32_bf16 v[48:51], v[158:161], v[190:193], v[48:51]
	v_mfma_f32_16x16x32_bf16 v[44:47], v[150:153], v[198:201], v[44:47]
	v_mfma_f32_16x16x32_bf16 v[40:43], v[158:161], v[198:201], v[40:43]
	v_mfma_f32_16x16x32_bf16 v[36:39], v[150:153], v[206:209], v[36:39]
	v_mfma_f32_16x16x32_bf16 v[32:35], v[158:161], v[206:209], v[32:35]
	v_mfma_f32_16x16x32_bf16 v[28:31], v[162:165], v[178:181], v[28:31]
	v_mfma_f32_16x16x32_bf16 v[24:27], v[170:173], v[178:181], v[24:27]
	v_mfma_f32_16x16x32_bf16 v[20:23], v[162:165], v[186:189], v[20:23]
	v_mfma_f32_16x16x32_bf16 v[16:19], v[170:173], v[186:189], v[16:19]
	v_mfma_f32_16x16x32_bf16 v[12:15], v[162:165], v[194:197], v[12:15]
	v_mfma_f32_16x16x32_bf16 v[8:11], v[170:173], v[194:197], v[8:11]
	v_mfma_f32_16x16x32_bf16 v[4:7], v[162:165], v[202:205], v[4:7]
	v_mfma_f32_16x16x32_bf16 v[0:3], v[170:173], v[202:205], v[0:3]
	v_mfma_f32_16x16x32_bf16 v[28:31], v[166:169], v[182:185], v[28:31]
	v_mfma_f32_16x16x32_bf16 v[24:27], v[174:177], v[182:185], v[24:27]
	v_mfma_f32_16x16x32_bf16 v[20:23], v[166:169], v[190:193], v[20:23]
	v_mfma_f32_16x16x32_bf16 v[16:19], v[174:177], v[190:193], v[16:19]
	v_mfma_f32_16x16x32_bf16 v[12:15], v[166:169], v[198:201], v[12:15]
	v_mfma_f32_16x16x32_bf16 v[8:11], v[174:177], v[198:201], v[8:11]
	v_mfma_f32_16x16x32_bf16 v[4:7], v[166:169], v[206:209], v[4:7]
	v_mfma_f32_16x16x32_bf16 v[0:3], v[174:177], v[206:209], v[0:3]
	s_barrier
; #define PG8_STAGE(bufoff, gbase, voff) do { _Pragma("unroll") for (int _i = 0; _i < 2; ++_i) \
;         __builtin_amdgcn_global_load_lds((const unsigned*)((const char*)(gbase) + (voff)[_i]), (PG8_LAS unsigned*)(lds + (bufoff) + ldsw + _i * 8192), 16, 0, 0); } while (0)
; #define PG8_LDA(dst, b, h) do { _Pragma("unroll") for (int m = 0; m < 4; ++m) _Pragma("unroll") for (int k = 0; k < 2; ++k) dst[m][k] = *(const PG8_LAS bf16x8*)(lds + PG8_SA(b, h) + aoff + m * 2048 + k * 1024); } while (0)
; #define PG8_LDB(dst, b, h) do { _Pragma("unroll") for (int n = 0; n < 2; ++n) _Pragma("unroll") for (int k = 0; k < 2; ++k) dst[n][k] = *(const PG8_LAS bf16x8*)(lds + PG8_SB(b, h) + boff + n * 2048 + k * 1024); } while (0)
; #define PG8_WAIT_V(n) asm volatile("s_waitcnt vmcnt(" #n ")" ::: "memory")
; #define PG8_WAIT_L(n) asm volatile("s_waitcnt lgkmcnt(" #n ")" ::: "memory")
; #define PG8_BAR __builtin_amdgcn_s_barrier()
; #define PG8_SCHED __builtin_amdgcn_sched_barrier(0)
; template <class Epi, class Sched, bool ALIGN_EPI = false, bool SP2 = false, bool F8 = false>
; __device__ __forceinline__ void gemm_phase(PG8_LAS unsigned char* lds, const int K, const Sched& S, const Epi& E, const int wave) {
;     ...
;             PG8_LDB(B0, 1, 0); PG8_LDB(B1, 1, 1); PG8_SCHED; PG8_LDA(At, 1, 0); PG8_STAGE(PG8_SA(0, 1), a2 + hstep, voffA);
;             PG8_WAIT_V(8); PG8_WAIT_L(0); PG8_BAR; PG8_MMA(0, 0, At, B0); PG8_MMA(0, 1, At, B1); PG8_BAR; PG8_SCHED;
;             PG8_LDA(At, 1, 1); PG8_STAGE(PG8_SB(1, 0), b3, voffB); PG8_STAGE(PG8_SB(1, 1), b3 + hstep, voffB); PG8_STAGE(PG8_SA(1, 0), a3, voffA);
;             PG8_WAIT_V(8); PG8_WAIT_L(0); PG8_BAR; PG8_MMA(1, 0, At, B0); PG8_MMA(1, 1, At, B1); PG8_BAR; PG8_SCHED;
.Lmid_k1240:
	s_setprio 0
	s_add_i32 s25, 0, 0x18000
	s_add_i32 s52, 0, 0x1c000
	ds_read_b128 v[140:143], v212
	ds_read_b128 v[150:153], v212 offset:1024
	ds_read_b128 v[154:157], v212 offset:2048
	ds_read_b128 v[158:161], v212 offset:3072
	ds_read_b128 v[162:165], v213
	ds_read_b128 v[166:169], v213 offset:1024
	ds_read_b128 v[170:173], v213 offset:2048
	ds_read_b128 v[174:177], v213 offset:3072
	s_add_u32 s44, s44, 0x100000
	s_addc_u32 s45, s45, 0
	s_mov_b32 m0, s51
	ds_read_b128 v[178:181], v148 offset:32768
	ds_read_b128 v[182:185], v148 offset:33792
	ds_read_b128 v[186:189], v148 offset:34816
	ds_read_b128 v[190:193], v148 offset:35840
	ds_read_b128 v[194:197], v148 offset:36864
	ds_read_b128 v[198:201], v148 offset:37888
	ds_read_b128 v[202:205], v148 offset:38912
	ds_read_b128 v[206:209], v148 offset:39936
	global_load_lds_dwordx4 v134, s[44:45]
	s_mov_b32 m0, s54
	s_nop 0
	global_load_lds_dwordx4 v130, s[44:45]
	s_waitcnt vmcnt(8)
	s_waitcnt lgkmcnt(0)
	s_setprio 1
	s_barrier
	v_mfma_f32_16x16x32_bf16 v[124:127], v[140:143], v[178:181], v[124:127]
	v_mfma_f32_16x16x32_bf16 v[120:123], v[154:157], v[178:181], v[120:123]
	v_mfma_f32_16x16x32_bf16 v[116:119], v[140:143], v[186:189], v[116:119]
	v_mfma_f32_16x16x32_bf16 v[112:115], v[154:157], v[186:189], v[112:115]
	v_mfma_f32_16x16x32_bf16 v[108:111], v[140:143], v[194:197], v[108:111]
	v_mfma_f32_16x16x32_bf16 v[104:107], v[154:157], v[194:197], v[104:107]
	v_mfma_f32_16x16x32_bf16 v[100:103], v[140:143], v[202:205], v[100:103]
	v_mfma_f32_16x16x32_bf16 v[96:99], v[154:157], v[202:205], v[96:99]
	v_mfma_f32_16x16x32_bf16 v[124:127], v[150:153], v[182:185], v[124:127]
	v_mfma_f32_16x16x32_bf16 v[120:123], v[158:161], v[182:185], v[120:123]
	v_mfma_f32_16x16x32_bf16 v[116:119], v[150:153], v[190:193], v[116:119]
	v_mfma_f32_16x16x32_bf16 v[112:115], v[158:161], v[190:193], v[112:115]
	v_mfma_f32_16x16x32_bf16 v[108:111], v[150:153], v[198:201], v[108:111]
	v_mfma_f32_16x16x32_bf16 v[104:107], v[158:161], v[198:201], v[104:107]
	v_mfma_f32_16x16x32_bf16 v[100:103], v[150:153], v[206:209], v[100:103]
	v_mfma_f32_16x16x32_bf16 v[96:99], v[158:161], v[206:209], v[96:99]
	v_mfma_f32_16x16x32_bf16 v[92:95], v[162:165], v[178:181], v[92:95]
	v_mfma_f32_16x16x32_bf16 v[88:91], v[170:173], v[178:181], v[88:91]
	v_mfma_f32_16x16x32_bf16 v[84:87], v[162:165], v[186:189], v[84:87]
	v_mfma_f32_16x16x32_bf16 v[80:83], v[170:173], v[186:189], v[80:83]
	v_mfma_f32_16x16x32_bf16 v[76:79], v[162:165], v[194:197], v[76:79]
	v_mfma_f32_16x16x32_bf16 v[72:75], v[170:173], v[194:197], v[72:75]
	v_mfma_f32_16x16x32_bf16 v[68:71], v[162:165], v[202:205], v[68:71]
	v_mfma_f32_16x16x32_bf16 v[64:67], v[170:173], v[202:205], v[64:67]
	v_mfma_f32_16x16x32_bf16 v[92:95], v[166:169], v[182:185], v[92:95]
	v_mfma_f32_16x16x32_bf16 v[88:91], v[174:177], v[182:185], v[88:91]
	v_mfma_f32_16x16x32_bf16 v[84:87], v[166:169], v[190:193], v[84:87]
	v_mfma_f32_16x16x32_bf16 v[80:83], v[174:177], v[190:193], v[80:83]
	v_mfma_f32_16x16x32_bf16 v[76:79], v[166:169], v[198:201], v[76:79]
	v_mfma_f32_16x16x32_bf16 v[72:75], v[174:177], v[198:201], v[72:75]
	v_mfma_f32_16x16x32_bf16 v[68:71], v[166:169], v[206:209], v[68:71]
	v_mfma_f32_16x16x32_bf16 v[64:67], v[174:177], v[206:209], v[64:67]
	s_barrier
	s_setprio 0
	s_add_i32 s25, s25, s48
	s_mov_b32 m0, s25
	ds_read_b128 v[178:181], v148 offset:49152
	ds_read_b128 v[182:185], v148 offset:50176
	ds_read_b128 v[186:189], v148 offset:51200
	ds_read_b128 v[190:193], v148 offset:52224
	ds_read_b128 v[194:197], v148 offset:53248
	ds_read_b128 v[198:201], v148 offset:54272
	ds_read_b128 v[202:205], v148 offset:55296
	ds_read_b128 v[206:209], v148 offset:56320
	global_load_lds_dwordx4 v132, s[42:43]
	s_add_i32 m0, s25, 0x2000
	s_nop 0
	global_load_lds_dwordx4 v128, s[42:43]
	s_add_u32 s42, s42, 0x100000
	s_addc_u32 s43, s43, 0
	s_add_i32 s25, s52, s48
	s_mov_b32 m0, s25
	s_nop 0
	global_load_lds_dwordx4 v132, s[42:43]
	s_add_i32 m0, s25, 0x2000
	s_nop 0
	global_load_lds_dwordx4 v128, s[42:43]
	s_mov_b32 m0, s55
	s_nop 0
	global_load_lds_dwordx4 v134, s[40:41]
	s_mov_b32 m0, s57
	s_nop 0
	global_load_lds_dwordx4 v130, s[40:41]
	s_waitcnt vmcnt(8)
	s_waitcnt lgkmcnt(0)
	s_setprio 1
	s_barrier
	v_mfma_f32_16x16x32_bf16 v[60:63], v[140:143], v[178:181], v[60:63]
	v_mfma_f32_16x16x32_bf16 v[56:59], v[154:157], v[178:181], v[56:59]
	v_mfma_f32_16x16x32_bf16 v[52:55], v[140:143], v[186:189], v[52:55]
	v_mfma_f32_16x16x32_bf16 v[48:51], v[154:157], v[186:189], v[48:51]
	v_mfma_f32_16x16x32_bf16 v[44:47], v[140:143], v[194:197], v[44:47]
	v_mfma_f32_16x16x32_bf16 v[40:43], v[154:157], v[194:197], v[40:43]
	v_mfma_f32_16x16x32_bf16 v[36:39], v[140:143], v[202:205], v[36:39]
	v_mfma_f32_16x16x32_bf16 v[32:35], v[154:157], v[202:205], v[32:35]
	v_mfma_f32_16x16x32_bf16 v[60:63], v[150:153], v[182:185], v[60:63]
	v_mfma_f32_16x16x32_bf16 v[56:59], v[158:161], v[182:185], v[56:59]
	v_mfma_f32_16x16x32_bf16 v[52:55], v[150:153], v[190:193], v[52:55]
	v_mfma_f32_16x16x32_bf16 v[48:51], v[158:161], v[190:193], v[48:51]
	v_mfma_f32_16x16x32_bf16 v[44:47], v[150:153], v[198:201], v[44:47]
	v_mfma_f32_16x16x32_bf16 v[40:43], v[158:161], v[198:201], v[40:43]
	v_mfma_f32_16x16x32_bf16 v[36:39], v[150:153], v[206:209], v[36:39]
	v_mfma_f32_16x16x32_bf16 v[32:35], v[158:161], v[206:209], v[32:35]
	v_mfma_f32_16x16x32_bf16 v[28:31], v[162:165], v[178:181], v[28:31]
	v_mfma_f32_16x16x32_bf16 v[24:27], v[170:173], v[178:181], v[24:27]
	v_mfma_f32_16x16x32_bf16 v[20:23], v[162:165], v[186:189], v[20:23]
	v_mfma_f32_16x16x32_bf16 v[16:19], v[170:173], v[186:189], v[16:19]
	v_mfma_f32_16x16x32_bf16 v[12:15], v[162:165], v[194:197], v[12:15]
	v_mfma_f32_16x16x32_bf16 v[8:11], v[170:173], v[194:197], v[8:11]
	v_mfma_f32_16x16x32_bf16 v[4:7], v[162:165], v[202:205], v[4:7]
	v_mfma_f32_16x16x32_bf16 v[0:3], v[170:173], v[202:205], v[0:3]
	v_mfma_f32_16x16x32_bf16 v[28:31], v[166:169], v[182:185], v[28:31]
	v_mfma_f32_16x16x32_bf16 v[24:27], v[174:177], v[182:185], v[24:27]
	v_mfma_f32_16x16x32_bf16 v[20:23], v[166:169], v[190:193], v[20:23]
	v_mfma_f32_16x16x32_bf16 v[16:19], v[174:177], v[190:193], v[16:19]
	v_mfma_f32_16x16x32_bf16 v[12:15], v[166:169], v[198:201], v[12:15]
	v_mfma_f32_16x16x32_bf16 v[8:11], v[174:177], v[198:201], v[8:11]
	v_mfma_f32_16x16x32_bf16 v[4:7], v[166:169], v[206:209], v[4:7]
	v_mfma_f32_16x16x32_bf16 v[0:3], v[174:177], v[206:209], v[0:3]
	s_barrier
	s_setprio 0
	s_add_i32 s23, s23, 2
	s_add_u32 s38, s38, 0x100
	s_addc_u32 s39, s39, 0
	s_cmp_gt_u32 s23, 61
	s_cbranch_scc0 .LBB0_1240
	s_and_b64 vcc, exec, s[18:19]
	s_cbranch_vccz .LBB0_1243
	s_barrier

; #define PG8_STAGE(bufoff, gbase, voff) do { _Pragma("unroll") for (int _i = 0; _i < 2; ++_i) \
;         __builtin_amdgcn_global_load_lds((const unsigned*)((const char*)(gbase) + (voff)[_i]), (PG8_LAS unsigned*)(lds + (bufoff) + ldsw + _i * 8192), 16, 0, 0); } while (0)
; #define PG8_LDA(dst, b, h) do { _Pragma("unroll") for (int m = 0; m < 4; ++m) _Pragma("unroll") for (int k = 0; k < 2; ++k) dst[m][k] = *(const PG8_LAS bf16x8*)(lds + PG8_SA(b, h) + aoff + m * 2048 + k * 1024); } while (0)
; #define PG8_LDB(dst, b, h) do { _Pragma("unroll") for (int n = 0; n < 2; ++n) _Pragma("unroll") for (int k = 0; k < 2; ++k) dst[n][k] = *(const PG8_LAS bf16x8*)(lds + PG8_SB(b, h) + boff + n * 2048 + k * 1024); } while (0)
; #define PG8_WAIT_V(n) asm volatile("s_waitcnt vmcnt(" #n ")" ::: "memory")
; #define PG8_WAIT_L(n) asm volatile("s_waitcnt lgkmcnt(" #n ")" ::: "memory")
; #define PG8_BAR __builtin_amdgcn_s_barrier()
; template <class Epi, class Sched, bool ALIGN_EPI = false, bool SP2 = false, bool F8 = false>
; __device__ __forceinline__ void gemm_phase(PG8_LAS unsigned char* lds, const int K, const Sched& S, const Epi& E, const int wave) {
;     ...
;             const bool last = (t == nt - 2);
;             const char* a1 = cA + (size_t)(t + 1) * kstep;
;             const char* a2 = last ? nA : cA + (size_t)(t + 2) * kstep; const char* b2 = last ? nB : cB + (size_t)(t + 2) * kstep;
;             const char* a3 = a2 + kstep; const char* b3 = b2 + kstep;
;             asm volatile("" : "+s"(a1), "+s"(a2), "+s"(b2), "+s"(a3), "+s"(b3));
;             if (last && has_next) S.a_ready(nxt);
;             if constexpr (Epi::KHOOK) { if (cur.prob == 2 ? (t == 16) : (t == 32 || t == 48)) { if (wr == 0) PG8_BAR;
;                 E.khook(acc, cur, (cur.prob == 2 || t == 48) ? 1 : 0, wr, wc, fr, fq); if (wr == 1) PG8_BAR; } }
;             if constexpr (SP2) {
;             PG8_LDB(B0, 0, 0); PG8_LDB(B1, 0, 1); PG8_SCHED; PG8_LDA(At, 0, 0); PG8_STAGE(PG8_SA(1, 1), a1 + hstep, voffA);
;             PG8_WAIT_V(8); PG8_WAIT_L(0); PG8_BAR; PG8_MMA(0, 0, At, B0); PG8_MMA(0, 1, At, B1); PG8_BAR; PG8_SCHED;
;             PG8_LDA(At, 0, 1); PG8_STAGE(PG8_SB(0, 0), b2, voffB); PG8_STAGE(PG8_SB(0, 1), b2 + hstep, voffB); PG8_STAGE(PG8_SA(0, 0), a2, voffA);
;             PG8_WAIT_V(8); PG8_WAIT_L(0); PG8_BAR; PG8_MMA(1, 0, At, B0); PG8_MMA(1, 1, At, B1); PG8_BAR; PG8_SCHED;
.Lpeel_k1348:
	v_add_u32_e32 v218, s67, v166
	v_add_u32_e32 v219, s72, v166
	v_add_u32_e32 v220, 0x18000, v166
	v_add_u32_e32 v221, 0x1c000, v166
	s_add_i32 s87, s8, 2
	s_cmp_eq_u32 s82, s8
	s_cselect_b32 s40, s79, s83
	s_cselect_b32 s41, s78, s84
	s_cselect_b32 s43, s80, s86
	s_cselect_b32 s42, s81, s85
	s_add_u32 s8, s40, 0x80
	s_addc_u32 s9, s41, 0
	s_add_u32 s38, s42, 0x80
	s_addc_u32 s39, s43, 0
	s_mov_b64 s[88:89], s[6:7]
	ds_read_b128 v[132:135], v218
	ds_read_b128 v[136:139], v218 offset:1024
	ds_read_b128 v[156:159], v218 offset:2048
	ds_read_b128 v[160:163], v218 offset:3072
	ds_read_b128 v[170:173], v219
	ds_read_b128 v[174:177], v219 offset:1024
	ds_read_b128 v[178:181], v219 offset:2048
	ds_read_b128 v[182:185], v219 offset:3072
	s_add_u32 s88, s88, 0x2b0000
	s_addc_u32 s89, s89, 0
	s_add_i32 m0, s58, 0xc000
	ds_read_b128 v[186:189], v168
	ds_read_b128 v[190:193], v168 offset:1024
	ds_read_b128 v[194:197], v168 offset:2048
	ds_read_b128 v[198:201], v168 offset:3072
	ds_read_b128 v[202:205], v168 offset:4096
	ds_read_b128 v[206:209], v168 offset:5120
	ds_read_b128 v[210:213], v168 offset:6144
	ds_read_b128 v[214:217], v168 offset:7168
	global_load_lds_dwordx4 v140, s[88:89]
	s_add_i32 m0, s58, 0xe000
	s_nop 0
	global_load_lds_dwordx4 v144, s[88:89]
	s_waitcnt vmcnt(8)
	s_waitcnt lgkmcnt(0)
	s_setprio 1
	s_barrier
	v_mfma_f32_16x16x32_bf16 v[128:131], v[132:135], v[186:189], 0
	v_mfma_f32_16x16x32_bf16 v[124:127], v[156:159], v[186:189], 0
	v_mfma_f32_16x16x32_bf16 v[120:123], v[132:135], v[194:197], 0
	v_mfma_f32_16x16x32_bf16 v[116:119], v[156:159], v[194:197], 0
	v_mfma_f32_16x16x32_bf16 v[112:115], v[132:135], v[202:205], 0
	v_mfma_f32_16x16x32_bf16 v[108:111], v[156:159], v[202:205], 0
	v_mfma_f32_16x16x32_bf16 v[104:107], v[132:135], v[210:213], 0
	v_mfma_f32_16x16x32_bf16 v[100:103], v[156:159], v[210:213], 0
	v_mfma_f32_16x16x32_bf16 v[128:131], v[136:139], v[190:193], v[128:131]
	v_mfma_f32_16x16x32_bf16 v[124:127], v[160:163], v[190:193], v[124:127]
	v_mfma_f32_16x16x32_bf16 v[120:123], v[136:139], v[198:201], v[120:123]
	v_mfma_f32_16x16x32_bf16 v[116:119], v[160:163], v[198:201], v[116:119]
	v_mfma_f32_16x16x32_bf16 v[112:115], v[136:139], v[206:209], v[112:115]
	v_mfma_f32_16x16x32_bf16 v[108:111], v[160:163], v[206:209], v[108:111]
	v_mfma_f32_16x16x32_bf16 v[104:107], v[136:139], v[214:217], v[104:107]
	v_mfma_f32_16x16x32_bf16 v[100:103], v[160:163], v[214:217], v[100:103]
	v_mfma_f32_16x16x32_bf16 v[96:99], v[170:173], v[186:189], 0
	v_mfma_f32_16x16x32_bf16 v[92:95], v[178:181], v[186:189], 0
	v_mfma_f32_16x16x32_bf16 v[88:91], v[170:173], v[194:197], 0
	v_mfma_f32_16x16x32_bf16 v[84:87], v[178:181], v[194:197], 0
	v_mfma_f32_16x16x32_bf16 v[80:83], v[170:173], v[202:205], 0
	v_mfma_f32_16x16x32_bf16 v[76:79], v[178:181], v[202:205], 0
	v_mfma_f32_16x16x32_bf16 v[72:75], v[170:173], v[210:213], 0
	v_mfma_f32_16x16x32_bf16 v[68:71], v[178:181], v[210:213], 0
	v_mfma_f32_16x16x32_bf16 v[96:99], v[174:177], v[190:193], v[96:99]
	v_mfma_f32_16x16x32_bf16 v[92:95], v[182:185], v[190:193], v[92:95]
	v_mfma_f32_16x16x32_bf16 v[88:91], v[174:177], v[198:201], v[88:91]
	v_mfma_f32_16x16x32_bf16 v[84:87], v[182:185], v[198:201], v[84:87]
	v_mfma_f32_16x16x32_bf16 v[80:83], v[174:177], v[206:209], v[80:83]
	v_mfma_f32_16x16x32_bf16 v[76:79], v[182:185], v[206:209], v[76:79]
	v_mfma_f32_16x16x32_bf16 v[72:75], v[174:177], v[214:217], v[72:75]
	v_mfma_f32_16x16x32_bf16 v[68:71], v[182:185], v[214:217], v[68:71]
	s_barrier
	s_setprio 0
	s_add_i32 s88, s67, s57
	s_mov_b32 m0, s88
	ds_read_b128 v[186:189], v168 offset:16384
	ds_read_b128 v[190:193], v168 offset:17408
	ds_read_b128 v[194:197], v168 offset:18432
	ds_read_b128 v[198:201], v168 offset:19456
	ds_read_b128 v[202:205], v168 offset:20480
	ds_read_b128 v[206:209], v168 offset:21504
	ds_read_b128 v[210:213], v168 offset:22528
	ds_read_b128 v[214:217], v168 offset:23552
	global_load_lds_dwordx4 v142, s[42:43]
	s_add_i32 m0, s88, 0x2000
	s_nop 0
	global_load_lds_dwordx4 v146, s[42:43]
	s_add_u32 s42, s42, 0x2b0000
	s_addc_u32 s43, s43, 0
	s_add_i32 s88, s72, s57
	s_mov_b32 m0, s88
	s_nop 0
	global_load_lds_dwordx4 v142, s[42:43]
	s_add_i32 m0, s88, 0x2000
	s_nop 0
	global_load_lds_dwordx4 v146, s[42:43]
	s_mov_b32 m0, s58
	s_nop 0
	global_load_lds_dwordx4 v140, s[40:41]
	s_mov_b32 m0, s59
	s_nop 0
	global_load_lds_dwordx4 v144, s[40:41]
	s_waitcnt vmcnt(8)
	s_waitcnt lgkmcnt(0)
	s_setprio 1
	s_barrier
	v_mfma_f32_16x16x32_bf16 v[64:67], v[132:135], v[186:189], 0
	v_mfma_f32_16x16x32_bf16 v[60:63], v[156:159], v[186:189], 0
	v_mfma_f32_16x16x32_bf16 v[56:59], v[132:135], v[194:197], 0
	v_mfma_f32_16x16x32_bf16 v[52:55], v[156:159], v[194:197], 0
	v_mfma_f32_16x16x32_bf16 v[48:51], v[132:135], v[202:205], 0
	v_mfma_f32_16x16x32_bf16 v[44:47], v[156:159], v[202:205], 0
	v_mfma_f32_16x16x32_bf16 v[40:43], v[132:135], v[210:213], 0
	v_mfma_f32_16x16x32_bf16 v[36:39], v[156:159], v[210:213], 0
	v_mfma_f32_16x16x32_bf16 v[64:67], v[136:139], v[190:193], v[64:67]
	v_mfma_f32_16x16x32_bf16 v[60:63], v[160:163], v[190:193], v[60:63]
	v_mfma_f32_16x16x32_bf16 v[56:59], v[136:139], v[198:201], v[56:59]
	v_mfma_f32_16x16x32_bf16 v[52:55], v[160:163], v[198:201], v[52:55]
	v_mfma_f32_16x16x32_bf16 v[48:51], v[136:139], v[206:209], v[48:51]
	v_mfma_f32_16x16x32_bf16 v[44:47], v[160:163], v[206:209], v[44:47]
	v_mfma_f32_16x16x32_bf16 v[40:43], v[136:139], v[214:217], v[40:43]
	v_mfma_f32_16x16x32_bf16 v[36:39], v[160:163], v[214:217], v[36:39]
	v_mfma_f32_16x16x32_bf16 v[32:35], v[170:173], v[186:189], 0
	v_mfma_f32_16x16x32_bf16 v[28:31], v[178:181], v[186:189], 0
	v_mfma_f32_16x16x32_bf16 v[24:27], v[170:173], v[194:197], 0
	v_mfma_f32_16x16x32_bf16 v[20:23], v[178:181], v[194:197], 0
	v_mfma_f32_16x16x32_bf16 v[16:19], v[170:173], v[202:205], 0
	v_mfma_f32_16x16x32_bf16 v[12:15], v[178:181], v[202:205], 0
	v_mfma_f32_16x16x32_bf16 v[8:11], v[170:173], v[210:213], 0
	v_mfma_f32_16x16x32_bf16 v[2:5], v[178:181], v[210:213], 0
	v_mfma_f32_16x16x32_bf16 v[32:35], v[174:177], v[190:193], v[32:35]
	v_mfma_f32_16x16x32_bf16 v[28:31], v[182:185], v[190:193], v[28:31]
	v_mfma_f32_16x16x32_bf16 v[24:27], v[174:177], v[198:201], v[24:27]
	v_mfma_f32_16x16x32_bf16 v[20:23], v[182:185], v[198:201], v[20:23]
	v_mfma_f32_16x16x32_bf16 v[16:19], v[174:177], v[206:209], v[16:19]
	v_mfma_f32_16x16x32_bf16 v[12:15], v[182:185], v[206:209], v[12:15]
	v_mfma_f32_16x16x32_bf16 v[8:11], v[174:177], v[214:217], v[8:11]
	v_mfma_f32_16x16x32_bf16 v[2:5], v[182:185], v[214:217], v[2:5]
	s_barrier
	s_branch .Lmid_k1348
; #define PG8_STAGE(bufoff, gbase, voff) do { _Pragma("unroll") for (int _i = 0; _i < 2; ++_i) \
;         __builtin_amdgcn_global_load_lds((const unsigned*)((const char*)(gbase) + (voff)[_i]), (PG8_LAS unsigned*)(lds + (bufoff) + ldsw + _i * 8192), 16, 0, 0); } while (0)
; #define PG8_LDA(dst, b, h) do { _Pragma("unroll") for (int m = 0; m < 4; ++m) _Pragma("unroll") for (int k = 0; k < 2; ++k) dst[m][k] = *(const PG8_LAS bf16x8*)(lds + PG8_SA(b, h) + aoff + m * 2048 + k * 1024); } while (0)
; #define PG8_LDB(dst, b, h) do { _Pragma("unroll") for (int n = 0; n < 2; ++n) _Pragma("unroll") for (int k = 0; k < 2; ++k) dst[n][k] = *(const PG8_LAS bf16x8*)(lds + PG8_SB(b, h) + boff + n * 2048 + k * 1024); } while (0)
; #define PG8_WAIT_V(n) asm volatile("s_waitcnt vmcnt(" #n ")" ::: "memory")
; #define PG8_WAIT_L(n) asm volatile("s_waitcnt lgkmcnt(" #n ")" ::: "memory")
; #define PG8_BAR __builtin_amdgcn_s_barrier()
; template <class Epi, class Sched, bool ALIGN_EPI = false, bool SP2 = false, bool F8 = false>
; __device__ __forceinline__ void gemm_phase(PG8_LAS unsigned char* lds, const int K, const Sched& S, const Epi& E, const int wave) {
;     ...
;             const bool last = (t == nt - 2);
;             const char* a1 = cA + (size_t)(t + 1) * kstep;
;             const char* a2 = last ? nA : cA + (size_t)(t + 2) * kstep; const char* b2 = last ? nB : cB + (size_t)(t + 2) * kstep;
;             const char* a3 = a2 + kstep; const char* b3 = b2 + kstep;
;             asm volatile("" : "+s"(a1), "+s"(a2), "+s"(b2), "+s"(a3), "+s"(b3));
;             if (last && has_next) S.a_ready(nxt);
;             if constexpr (Epi::KHOOK) { if (cur.prob == 2 ? (t == 16) : (t == 32 || t == 48)) { if (wr == 0) PG8_BAR;
;                 E.khook(acc, cur, (cur.prob == 2 || t == 48) ? 1 : 0, wr, wc, fr, fq); if (wr == 1) PG8_BAR; } }
;             if constexpr (SP2) {
;             PG8_LDB(B0, 0, 0); PG8_LDB(B1, 0, 1); PG8_SCHED; PG8_LDA(At, 0, 0); PG8_STAGE(PG8_SA(1, 1), a1 + hstep, voffA);
;             PG8_WAIT_V(8); PG8_WAIT_L(0); PG8_BAR; PG8_MMA(0, 0, At, B0); PG8_MMA(0, 1, At, B1); PG8_BAR; PG8_SCHED;
;             PG8_LDA(At, 0, 1); PG8_STAGE(PG8_SB(0, 0), b2, voffB); PG8_STAGE(PG8_SB(0, 1), b2 + hstep, voffB); PG8_STAGE(PG8_SA(0, 0), a2, voffA);
;             PG8_WAIT_V(8); PG8_WAIT_L(0); PG8_BAR; PG8_MMA(1, 0, At, B0); PG8_MMA(1, 1, At, B1); PG8_BAR; PG8_SCHED;
.LBB0_1348:
	s_add_i32 s87, s8, 2
	s_cmp_eq_u32 s82, s8
	s_cselect_b32 s40, s79, s83
	s_cselect_b32 s41, s78, s84
	s_cselect_b32 s43, s80, s86
	s_cselect_b32 s42, s81, s85
	s_add_u32 s8, s40, 0x80
	s_addc_u32 s9, s41, 0
	s_add_u32 s38, s42, 0x80
	s_addc_u32 s39, s43, 0
	s_mov_b64 s[88:89], s[6:7]
	ds_read_b128 v[132:135], v218
	ds_read_b128 v[136:139], v218 offset:1024
	ds_read_b128 v[156:159], v218 offset:2048
	ds_read_b128 v[160:163], v218 offset:3072
	ds_read_b128 v[170:173], v219
	ds_read_b128 v[174:177], v219 offset:1024
	ds_read_b128 v[178:181], v219 offset:2048
	ds_read_b128 v[182:185], v219 offset:3072
	s_add_u32 s88, s88, 0x2b0000
	s_addc_u32 s89, s89, 0
	s_add_i32 m0, s58, 0xc000
	ds_read_b128 v[186:189], v168
	ds_read_b128 v[190:193], v168 offset:1024
	ds_read_b128 v[194:197], v168 offset:2048
	ds_read_b128 v[198:201], v168 offset:3072
	ds_read_b128 v[202:205], v168 offset:4096
	ds_read_b128 v[206:209], v168 offset:5120
	ds_read_b128 v[210:213], v168 offset:6144
	ds_read_b128 v[214:217], v168 offset:7168
	global_load_lds_dwordx4 v140, s[88:89]
	s_add_i32 m0, s58, 0xe000
	s_nop 0
	global_load_lds_dwordx4 v144, s[88:89]
	s_waitcnt vmcnt(8)
	s_waitcnt lgkmcnt(0)
	s_setprio 1
	s_barrier
	v_mfma_f32_16x16x32_bf16 v[128:131], v[132:135], v[186:189], v[128:131]
	v_mfma_f32_16x16x32_bf16 v[124:127], v[156:159], v[186:189], v[124:127]
	v_mfma_f32_16x16x32_bf16 v[120:123], v[132:135], v[194:197], v[120:123]
	v_mfma_f32_16x16x32_bf16 v[116:119], v[156:159], v[194:197], v[116:119]
	v_mfma_f32_16x16x32_bf16 v[112:115], v[132:135], v[202:205], v[112:115]
	v_mfma_f32_16x16x32_bf16 v[108:111], v[156:159], v[202:205], v[108:111]
	v_mfma_f32_16x16x32_bf16 v[104:107], v[132:135], v[210:213], v[104:107]
	v_mfma_f32_16x16x32_bf16 v[100:103], v[156:159], v[210:213], v[100:103]
	v_mfma_f32_16x16x32_bf16 v[128:131], v[136:139], v[190:193], v[128:131]
	v_mfma_f32_16x16x32_bf16 v[124:127], v[160:163], v[190:193], v[124:127]
	v_mfma_f32_16x16x32_bf16 v[120:123], v[136:139], v[198:201], v[120:123]
	v_mfma_f32_16x16x32_bf16 v[116:119], v[160:163], v[198:201], v[116:119]
	v_mfma_f32_16x16x32_bf16 v[112:115], v[136:139], v[206:209], v[112:115]
	v_mfma_f32_16x16x32_bf16 v[108:111], v[160:163], v[206:209], v[108:111]
	v_mfma_f32_16x16x32_bf16 v[104:107], v[136:139], v[214:217], v[104:107]
	v_mfma_f32_16x16x32_bf16 v[100:103], v[160:163], v[214:217], v[100:103]
	v_mfma_f32_16x16x32_bf16 v[96:99], v[170:173], v[186:189], v[96:99]
	v_mfma_f32_16x16x32_bf16 v[92:95], v[178:181], v[186:189], v[92:95]
	v_mfma_f32_16x16x32_bf16 v[88:91], v[170:173], v[194:197], v[88:91]
	v_mfma_f32_16x16x32_bf16 v[84:87], v[178:181], v[194:197], v[84:87]
	v_mfma_f32_16x16x32_bf16 v[80:83], v[170:173], v[202:205], v[80:83]
	v_mfma_f32_16x16x32_bf16 v[76:79], v[178:181], v[202:205], v[76:79]
	v_mfma_f32_16x16x32_bf16 v[72:75], v[170:173], v[210:213], v[72:75]
	v_mfma_f32_16x16x32_bf16 v[68:71], v[178:181], v[210:213], v[68:71]
	v_mfma_f32_16x16x32_bf16 v[96:99], v[174:177], v[190:193], v[96:99]
	v_mfma_f32_16x16x32_bf16 v[92:95], v[182:185], v[190:193], v[92:95]
	v_mfma_f32_16x16x32_bf16 v[88:91], v[174:177], v[198:201], v[88:91]
	v_mfma_f32_16x16x32_bf16 v[84:87], v[182:185], v[198:201], v[84:87]
	v_mfma_f32_16x16x32_bf16 v[80:83], v[174:177], v[206:209], v[80:83]
	v_mfma_f32_16x16x32_bf16 v[76:79], v[182:185], v[206:209], v[76:79]
	v_mfma_f32_16x16x32_bf16 v[72:75], v[174:177], v[214:217], v[72:75]
	v_mfma_f32_16x16x32_bf16 v[68:71], v[182:185], v[214:217], v[68:71]
	s_barrier
	s_setprio 0
	s_add_i32 s88, s67, s57
	s_mov_b32 m0, s88
	ds_read_b128 v[186:189], v168 offset:16384
	ds_read_b128 v[190:193], v168 offset:17408
	ds_read_b128 v[194:197], v168 offset:18432
	ds_read_b128 v[198:201], v168 offset:19456
	ds_read_b128 v[202:205], v168 offset:20480
	ds_read_b128 v[206:209], v168 offset:21504
	ds_read_b128 v[210:213], v168 offset:22528
	ds_read_b128 v[214:217], v168 offset:23552
	global_load_lds_dwordx4 v142, s[42:43]
	s_add_i32 m0, s88, 0x2000
	s_nop 0
	global_load_lds_dwordx4 v146, s[42:43]
	s_add_u32 s42, s42, 0x2b0000
	s_addc_u32 s43, s43, 0
	s_add_i32 s88, s72, s57
	s_mov_b32 m0, s88
	s_nop 0
	global_load_lds_dwordx4 v142, s[42:43]
	s_add_i32 m0, s88, 0x2000
	s_nop 0
	global_load_lds_dwordx4 v146, s[42:43]
	s_mov_b32 m0, s58
	s_nop 0
	global_load_lds_dwordx4 v140, s[40:41]
	s_mov_b32 m0, s59
	s_nop 0
	global_load_lds_dwordx4 v144, s[40:41]
	s_waitcnt vmcnt(8)
	s_waitcnt lgkmcnt(0)
	s_setprio 1
	s_barrier
	v_mfma_f32_16x16x32_bf16 v[64:67], v[132:135], v[186:189], v[64:67]
	v_mfma_f32_16x16x32_bf16 v[60:63], v[156:159], v[186:189], v[60:63]
	v_mfma_f32_16x16x32_bf16 v[56:59], v[132:135], v[194:197], v[56:59]
	v_mfma_f32_16x16x32_bf16 v[52:55], v[156:159], v[194:197], v[52:55]
	v_mfma_f32_16x16x32_bf16 v[48:51], v[132:135], v[202:205], v[48:51]
	v_mfma_f32_16x16x32_bf16 v[44:47], v[156:159], v[202:205], v[44:47]
	v_mfma_f32_16x16x32_bf16 v[40:43], v[132:135], v[210:213], v[40:43]
	v_mfma_f32_16x16x32_bf16 v[36:39], v[156:159], v[210:213], v[36:39]
	v_mfma_f32_16x16x32_bf16 v[64:67], v[136:139], v[190:193], v[64:67]
	v_mfma_f32_16x16x32_bf16 v[60:63], v[160:163], v[190:193], v[60:63]
	v_mfma_f32_16x16x32_bf16 v[56:59], v[136:139], v[198:201], v[56:59]
	v_mfma_f32_16x16x32_bf16 v[52:55], v[160:163], v[198:201], v[52:55]
	v_mfma_f32_16x16x32_bf16 v[48:51], v[136:139], v[206:209], v[48:51]
	v_mfma_f32_16x16x32_bf16 v[44:47], v[160:163], v[206:209], v[44:47]
	v_mfma_f32_16x16x32_bf16 v[40:43], v[136:139], v[214:217], v[40:43]
	v_mfma_f32_16x16x32_bf16 v[36:39], v[160:163], v[214:217], v[36:39]
	v_mfma_f32_16x16x32_bf16 v[32:35], v[170:173], v[186:189], v[32:35]
	v_mfma_f32_16x16x32_bf16 v[28:31], v[178:181], v[186:189], v[28:31]
	v_mfma_f32_16x16x32_bf16 v[24:27], v[170:173], v[194:197], v[24:27]
	v_mfma_f32_16x16x32_bf16 v[20:23], v[178:181], v[194:197], v[20:23]
	v_mfma_f32_16x16x32_bf16 v[16:19], v[170:173], v[202:205], v[16:19]
	v_mfma_f32_16x16x32_bf16 v[12:15], v[178:181], v[202:205], v[12:15]
	v_mfma_f32_16x16x32_bf16 v[8:11], v[170:173], v[210:213], v[8:11]
	v_mfma_f32_16x16x32_bf16 v[2:5], v[178:181], v[210:213], v[4:7]
	v_mfma_f32_16x16x32_bf16 v[32:35], v[174:177], v[190:193], v[32:35]
	v_mfma_f32_16x16x32_bf16 v[28:31], v[182:185], v[190:193], v[28:31]
	v_mfma_f32_16x16x32_bf16 v[24:27], v[174:177], v[198:201], v[24:27]
	v_mfma_f32_16x16x32_bf16 v[20:23], v[182:185], v[198:201], v[20:23]
	v_mfma_f32_16x16x32_bf16 v[16:19], v[174:177], v[206:209], v[16:19]
	v_mfma_f32_16x16x32_bf16 v[12:15], v[182:185], v[206:209], v[12:15]
	v_mfma_f32_16x16x32_bf16 v[8:11], v[174:177], v[214:217], v[8:11]
	v_mfma_f32_16x16x32_bf16 v[2:5], v[182:185], v[214:217], v[2:5]
	s_barrier
; #define PG8_STAGE(bufoff, gbase, voff) do { _Pragma("unroll") for (int _i = 0; _i < 2; ++_i) \
;         __builtin_amdgcn_global_load_lds((const unsigned*)((const char*)(gbase) + (voff)[_i]), (PG8_LAS unsigned*)(lds + (bufoff) + ldsw + _i * 8192), 16, 0, 0); } while (0)
; #define PG8_LDA(dst, b, h) do { _Pragma("unroll") for (int m = 0; m < 4; ++m) _Pragma("unroll") for (int k = 0; k < 2; ++k) dst[m][k] = *(const PG8_LAS bf16x8*)(lds + PG8_SA(b, h) + aoff + m * 2048 + k * 1024); } while (0)
; #define PG8_LDB(dst, b, h) do { _Pragma("unroll") for (int n = 0; n < 2; ++n) _Pragma("unroll") for (int k = 0; k < 2; ++k) dst[n][k] = *(const PG8_LAS bf16x8*)(lds + PG8_SB(b, h) + boff + n * 2048 + k * 1024); } while (0)
; #define PG8_WAIT_V(n) asm volatile("s_waitcnt vmcnt(" #n ")" ::: "memory")
; #define PG8_WAIT_L(n) asm volatile("s_waitcnt lgkmcnt(" #n ")" ::: "memory")
; #define PG8_BAR __builtin_amdgcn_s_barrier()
; #define PG8_SCHED __builtin_amdgcn_sched_barrier(0)
; template <class Epi, class Sched, bool ALIGN_EPI = false, bool SP2 = false, bool F8 = false>
; __device__ __forceinline__ void gemm_phase(PG8_LAS unsigned char* lds, const int K, const Sched& S, const Epi& E, const int wave) {
;     ...
;             PG8_LDB(B0, 1, 0); PG8_LDB(B1, 1, 1); PG8_SCHED; PG8_LDA(At, 1, 0); PG8_STAGE(PG8_SA(0, 1), a2 + hstep, voffA);
;             PG8_WAIT_V(8); PG8_WAIT_L(0); PG8_BAR; PG8_MMA(0, 0, At, B0); PG8_MMA(0, 1, At, B1); PG8_BAR; PG8_SCHED;
;             PG8_LDA(At, 1, 1); PG8_STAGE(PG8_SB(1, 0), b3, voffB); PG8_STAGE(PG8_SB(1, 1), b3 + hstep, voffB); PG8_STAGE(PG8_SA(1, 0), a3, voffA);
;             PG8_WAIT_V(8); PG8_WAIT_L(0); PG8_BAR; PG8_MMA(1, 0, At, B0); PG8_MMA(1, 1, At, B1); PG8_BAR; PG8_SCHED;
.Lmid_k1348:
	s_setprio 0
	s_add_i32 s42, 0, 0x18000
	s_add_i32 s43, 0, 0x1c000
	ds_read_b128 v[132:135], v220
	ds_read_b128 v[136:139], v220 offset:1024
	ds_read_b128 v[156:159], v220 offset:2048
	ds_read_b128 v[160:163], v220 offset:3072
	ds_read_b128 v[170:173], v221
	ds_read_b128 v[174:177], v221 offset:1024
	ds_read_b128 v[178:181], v221 offset:2048
	ds_read_b128 v[182:185], v221 offset:3072
	s_add_u32 s40, s40, 0x2b0000
	s_addc_u32 s41, s41, 0
	s_mov_b32 m0, s60
	ds_read_b128 v[186:189], v168 offset:32768
	ds_read_b128 v[190:193], v168 offset:33792
	ds_read_b128 v[194:197], v168 offset:34816
	ds_read_b128 v[198:201], v168 offset:35840
	ds_read_b128 v[202:205], v168 offset:36864
	ds_read_b128 v[206:209], v168 offset:37888
	ds_read_b128 v[210:213], v168 offset:38912
	ds_read_b128 v[214:217], v168 offset:39936
	global_load_lds_dwordx4 v140, s[40:41]
	s_mov_b32 m0, s61
	s_nop 0
	global_load_lds_dwordx4 v144, s[40:41]
	s_waitcnt vmcnt(8)
	s_waitcnt lgkmcnt(0)
	s_setprio 1
	s_barrier
	v_mfma_f32_16x16x32_bf16 v[128:131], v[132:135], v[186:189], v[128:131]
	v_mfma_f32_16x16x32_bf16 v[124:127], v[156:159], v[186:189], v[124:127]
	v_mfma_f32_16x16x32_bf16 v[120:123], v[132:135], v[194:197], v[120:123]
	v_mfma_f32_16x16x32_bf16 v[116:119], v[156:159], v[194:197], v[116:119]
	v_mfma_f32_16x16x32_bf16 v[112:115], v[132:135], v[202:205], v[112:115]
	v_mfma_f32_16x16x32_bf16 v[108:111], v[156:159], v[202:205], v[108:111]
	v_mfma_f32_16x16x32_bf16 v[104:107], v[132:135], v[210:213], v[104:107]
	v_mfma_f32_16x16x32_bf16 v[100:103], v[156:159], v[210:213], v[100:103]
	v_mfma_f32_16x16x32_bf16 v[128:131], v[136:139], v[190:193], v[128:131]
	v_mfma_f32_16x16x32_bf16 v[124:127], v[160:163], v[190:193], v[124:127]
	v_mfma_f32_16x16x32_bf16 v[120:123], v[136:139], v[198:201], v[120:123]
	v_mfma_f32_16x16x32_bf16 v[116:119], v[160:163], v[198:201], v[116:119]
	v_mfma_f32_16x16x32_bf16 v[112:115], v[136:139], v[206:209], v[112:115]
	v_mfma_f32_16x16x32_bf16 v[108:111], v[160:163], v[206:209], v[108:111]
	v_mfma_f32_16x16x32_bf16 v[104:107], v[136:139], v[214:217], v[104:107]
	v_mfma_f32_16x16x32_bf16 v[100:103], v[160:163], v[214:217], v[100:103]
	v_mfma_f32_16x16x32_bf16 v[96:99], v[170:173], v[186:189], v[96:99]
	v_mfma_f32_16x16x32_bf16 v[92:95], v[178:181], v[186:189], v[92:95]
	v_mfma_f32_16x16x32_bf16 v[88:91], v[170:173], v[194:197], v[88:91]
	v_mfma_f32_16x16x32_bf16 v[84:87], v[178:181], v[194:197], v[84:87]
	v_mfma_f32_16x16x32_bf16 v[80:83], v[170:173], v[202:205], v[80:83]
	v_mfma_f32_16x16x32_bf16 v[76:79], v[178:181], v[202:205], v[76:79]
	v_mfma_f32_16x16x32_bf16 v[72:75], v[170:173], v[210:213], v[72:75]
	v_mfma_f32_16x16x32_bf16 v[68:71], v[178:181], v[210:213], v[68:71]
	v_mfma_f32_16x16x32_bf16 v[96:99], v[174:177], v[190:193], v[96:99]
	v_mfma_f32_16x16x32_bf16 v[92:95], v[182:185], v[190:193], v[92:95]
	v_mfma_f32_16x16x32_bf16 v[88:91], v[174:177], v[198:201], v[88:91]
	v_mfma_f32_16x16x32_bf16 v[84:87], v[182:185], v[198:201], v[84:87]
	v_mfma_f32_16x16x32_bf16 v[80:83], v[174:177], v[206:209], v[80:83]
	v_mfma_f32_16x16x32_bf16 v[76:79], v[182:185], v[206:209], v[76:79]
	v_mfma_f32_16x16x32_bf16 v[72:75], v[174:177], v[214:217], v[72:75]
	v_mfma_f32_16x16x32_bf16 v[68:71], v[182:185], v[214:217], v[68:71]
	s_barrier
	s_setprio 0
	s_add_i32 s40, s42, s57
	s_mov_b32 m0, s40
	ds_read_b128 v[186:189], v168 offset:49152
	ds_read_b128 v[190:193], v168 offset:50176
	ds_read_b128 v[194:197], v168 offset:51200
	ds_read_b128 v[198:201], v168 offset:52224
	ds_read_b128 v[202:205], v168 offset:53248
	ds_read_b128 v[206:209], v168 offset:54272
	ds_read_b128 v[210:213], v168 offset:55296
	ds_read_b128 v[214:217], v168 offset:56320
	global_load_lds_dwordx4 v142, s[38:39]
	s_add_i32 m0, s40, 0x2000
	s_nop 0
	global_load_lds_dwordx4 v146, s[38:39]
	s_add_u32 s38, s38, 0x2b0000
	s_addc_u32 s39, s39, 0
	s_add_i32 s40, s43, s57
	s_mov_b32 m0, s40
	s_nop 0
	global_load_lds_dwordx4 v142, s[38:39]
	s_add_i32 m0, s40, 0x2000
	s_nop 0
	global_load_lds_dwordx4 v146, s[38:39]
	s_mov_b32 m0, s65
	s_nop 0
	global_load_lds_dwordx4 v140, s[8:9]
	s_mov_b32 m0, s66
	s_nop 0
	global_load_lds_dwordx4 v144, s[8:9]
	s_waitcnt vmcnt(8)
	s_waitcnt lgkmcnt(0)
	s_setprio 1
	s_barrier
	v_mfma_f32_16x16x32_bf16 v[64:67], v[132:135], v[186:189], v[64:67]
	v_mfma_f32_16x16x32_bf16 v[60:63], v[156:159], v[186:189], v[60:63]
	v_mfma_f32_16x16x32_bf16 v[56:59], v[132:135], v[194:197], v[56:59]
	v_mfma_f32_16x16x32_bf16 v[52:55], v[156:159], v[194:197], v[52:55]
	v_mfma_f32_16x16x32_bf16 v[48:51], v[132:135], v[202:205], v[48:51]
	v_mfma_f32_16x16x32_bf16 v[44:47], v[156:159], v[202:205], v[44:47]
	v_mfma_f32_16x16x32_bf16 v[40:43], v[132:135], v[210:213], v[40:43]
	v_mfma_f32_16x16x32_bf16 v[36:39], v[156:159], v[210:213], v[36:39]
	v_mfma_f32_16x16x32_bf16 v[64:67], v[136:139], v[190:193], v[64:67]
	v_mfma_f32_16x16x32_bf16 v[60:63], v[160:163], v[190:193], v[60:63]
	v_mfma_f32_16x16x32_bf16 v[56:59], v[136:139], v[198:201], v[56:59]
	v_mfma_f32_16x16x32_bf16 v[52:55], v[160:163], v[198:201], v[52:55]
	v_mfma_f32_16x16x32_bf16 v[48:51], v[136:139], v[206:209], v[48:51]
	v_mfma_f32_16x16x32_bf16 v[44:47], v[160:163], v[206:209], v[44:47]
	v_mfma_f32_16x16x32_bf16 v[40:43], v[136:139], v[214:217], v[40:43]
	v_mfma_f32_16x16x32_bf16 v[36:39], v[160:163], v[214:217], v[36:39]
	v_mfma_f32_16x16x32_bf16 v[32:35], v[170:173], v[186:189], v[32:35]
	v_mfma_f32_16x16x32_bf16 v[28:31], v[178:181], v[186:189], v[28:31]
	v_mfma_f32_16x16x32_bf16 v[24:27], v[170:173], v[194:197], v[24:27]
	v_mfma_f32_16x16x32_bf16 v[20:23], v[178:181], v[194:197], v[20:23]
	v_mfma_f32_16x16x32_bf16 v[16:19], v[170:173], v[202:205], v[16:19]
	v_mfma_f32_16x16x32_bf16 v[12:15], v[178:181], v[202:205], v[12:15]
	v_mfma_f32_16x16x32_bf16 v[6:9], v[170:173], v[210:213], v[8:11]
	v_mfma_f32_16x16x32_bf16 v[2:5], v[178:181], v[210:213], v[2:5]
	v_mfma_f32_16x16x32_bf16 v[32:35], v[174:177], v[190:193], v[32:35]
	v_mfma_f32_16x16x32_bf16 v[28:31], v[182:185], v[190:193], v[28:31]
	v_mfma_f32_16x16x32_bf16 v[24:27], v[174:177], v[198:201], v[24:27]
	v_mfma_f32_16x16x32_bf16 v[20:23], v[182:185], v[198:201], v[20:23]
	v_mfma_f32_16x16x32_bf16 v[16:19], v[174:177], v[206:209], v[16:19]
	v_mfma_f32_16x16x32_bf16 v[12:15], v[182:185], v[206:209], v[12:15]
	v_mfma_f32_16x16x32_bf16 v[8:11], v[174:177], v[214:217], v[6:9]
	v_mfma_f32_16x16x32_bf16 v[4:7], v[182:185], v[214:217], v[2:5]
	s_barrier
	s_setprio 0
	s_add_u32 s83, s83, 0x100
	s_addc_u32 s84, s84, 0
	s_add_u32 s85, s85, 0x100
	s_addc_u32 s86, s86, 0
	s_add_u32 s6, s6, 0x100
	s_addc_u32 s7, s7, 0
	s_cmp_ge_i32 s87, s56
	s_mov_b32 s8, s87
	s_cbranch_scc0 .LBB0_1348
